# first K-iteration of the P1/P5/P6/P7 K-loops peeled: first-touch MFMAs take an inline 0 as SrcC, the 128-instruction per-tile accumulator zeroing is gone
# baseline (speedup 1.0000x reference)
;     __device__ bool next(int i, Unit& u) const { if (i >= 2) return false; const int x = c & 7, j = c >> 3; u.pm = 8 * x + (j >> 3) + 4 * i; u.pn = j & 7; return true; }
; #define PG8_STAGE(bufoff, gbase, voff) do { _Pragma("unroll") for (int _i = 0; _i < 2; ++_i) \
;         __builtin_amdgcn_global_load_lds((const unsigned*)((const char*)(gbase) + (voff)[_i]), (LAS unsigned*)(lds + (bufoff) + ldsw + _i * 8192), 16, 0, 0); } while (0)
; #define PG8_LDA(dst, b, h) do { _Pragma("unroll") for (int m = 0; m < 4; ++m) _Pragma("unroll") for (int k = 0; k < 2; ++k) dst[m][k] = *(const LAS bf16x8*)(lds + PG8_SA(b, h) + aoff + m * 2048 + k * 1024); } while (0)
; #define PG8_LDB(dst, b, h) do { _Pragma("unroll") for (int n = 0; n < 2; ++n) _Pragma("unroll") for (int k = 0; k < 2; ++k) dst[n][k] = *(const LAS bf16x8*)(lds + PG8_SB(b, h) + boff + n * 2048 + k * 1024); } while (0)
; #define PG8_WAIT_V(n) asm volatile("s_waitcnt vmcnt(" #n ")" ::: "memory")
; #define PG8_WAIT_L(n) asm volatile("s_waitcnt lgkmcnt(" #n ")" ::: "memory")
; #define PG8_BAR __builtin_amdgcn_s_barrier()
; template <class Epi, class Sched>
; __device__ __forceinline__ void gemm_phase(LAS unsigned char* lds, const Gemm g, const Sched& S, const Epi& E) {
;     ...
;         const bool has_next = S.next(ui + 1, nxt);
;         const char* nA = has_next ? PG8_ABASE(nxt) : cA; const char* nB = has_next ? PG8_BBASE(nxt) : cB;
; #pragma unroll 1
;         for (int t = 0; t < nt; t += 2) {
;             if constexpr (Epi::MIDT >= 0) {
;                 if (t == Epi::MIDT) { int fr_m = fr, fq_m = fq; asm volatile("" : "+v"(fr_m), "+v"(fq_m)); E.mid(acc, cur, wr, wc, fr_m, fq_m); }
;             }
;             const bool last = (t == nt - 2);
;             const char* a1 = cA + (size_t)(t + 1) * kstep;
;             const char* a2 = last ? nA : cA + (size_t)(t + 2) * kstep; const char* b2 = last ? nB : cB + (size_t)(t + 2) * kstep;
;             const char* a3 = a2 + kstep; const char* b3 = b2 + kstep;
;             PG8_LDB(B0, 0, 0); PG8_LDB(B1, 0, 1); PG8_SCHED; PG8_LDA(At, 0, 0); PG8_STAGE(PG8_SA(1, 1), a1 + hstepA, voffA);
;             PG8_WAIT_V(8); PG8_WAIT_L(0); PG8_BAR; PG8_MMA(0, 0, At, B0); PG8_MMA(0, 1, At, B1); PG8_BAR; PG8_SCHED;
;             PG8_LDA(At, 0, 1); PG8_STAGE(PG8_SB(0, 0), b2, voffB); PG8_STAGE(PG8_SB(0, 1), b2 + hstepB, voffB); PG8_STAGE(PG8_SA(0, 0), a2, voffA);
.LBB0_121:
	s_ashr_i32 s87, s86, 31
	s_lshl_b64 s[6:7], s[86:87], 20
	s_add_u32 s92, s40, s6
	s_addc_u32 s93, s41, s7
	s_and_b64 s[6:7], s[90:91], exec
	s_cselect_b32 s8, s93, s1
	s_cselect_b32 s9, s92, s0
	s_ashr_i32 s89, s88, 31
	s_lshl_b64 s[6:7], s[88:89], 20
	s_add_u32 s94, s70, s6
	s_addc_u32 s95, s71, s7
	s_and_b64 s[6:7], s[90:91], exec
	s_cselect_b32 s10, s95, s5
	s_cselect_b32 s11, s94, s4
	s_add_u32 s0, s0, 0x80080
	s_addc_u32 s1, s1, 0
	s_add_u32 s34, s4, 0x100
	s_addc_u32 s35, s5, 0
	s_mov_b32 s87, -2
	ds_read_b128 v[128:131], v209
	ds_read_b128 v[132:135], v209 offset:1024
	ds_read_b128 v[136:139], v209 offset:2048
	ds_read_b128 v[140:143], v209 offset:3072
	ds_read_b128 v[144:147], v210
	ds_read_b128 v[148:151], v210 offset:1024
	ds_read_b128 v[152:155], v210 offset:2048
	ds_read_b128 v[156:159], v210 offset:3072
	s_add_u32 s4, s0, 0xfff80080
	s_addc_u32 s5, s1, -1
	s_cmp_eq_u32 s87, 28
	s_cselect_b32 s7, s8, s5
	s_cselect_b32 s6, s9, s4
	s_cselect_b32 s5, s10, s35
	s_cselect_b32 s4, s11, s34
	v_lshl_add_u64 v[216:217], s[0:1], 0, v[178:179]
	s_add_i32 m0, s15, 0xc000
	ds_read_b128 v[160:163], v211
	ds_read_b128 v[164:167], v211 offset:1024
	ds_read_b128 v[182:185], v211 offset:2048
	ds_read_b128 v[186:189], v211 offset:3072
	ds_read_b128 v[190:193], v211 offset:4096
	ds_read_b128 v[194:197], v211 offset:5120
	ds_read_b128 v[198:201], v211 offset:6144
	ds_read_b128 v[202:205], v211 offset:7168
	global_load_lds_dwordx4 v[216:217], off
	v_lshl_add_u64 v[216:217], s[0:1], 0, v[180:181]
	s_add_i32 m0, s15, 0xe000
	s_nop 0
	global_load_lds_dwordx4 v[216:217], off
	s_waitcnt vmcnt(8) lgkmcnt(0)
	s_barrier
	s_setprio 1
	v_mfma_f32_16x16x32_bf16 v[124:127], v[128:131], v[160:163], 0
	v_mfma_f32_16x16x32_bf16 v[120:123], v[136:139], v[160:163], 0
	v_mfma_f32_16x16x32_bf16 v[116:119], v[128:131], v[182:185], 0
	v_mfma_f32_16x16x32_bf16 v[112:115], v[136:139], v[182:185], 0
	v_mfma_f32_16x16x32_bf16 v[108:111], v[128:131], v[190:193], 0
	v_mfma_f32_16x16x32_bf16 v[104:107], v[136:139], v[190:193], 0
	v_mfma_f32_16x16x32_bf16 v[96:99], v[128:131], v[198:201], 0
	v_mfma_f32_16x16x32_bf16 v[100:103], v[136:139], v[198:201], 0
	v_mfma_f32_16x16x32_bf16 v[124:127], v[132:135], v[164:167], v[124:127]
	v_mfma_f32_16x16x32_bf16 v[120:123], v[140:143], v[164:167], v[120:123]
	v_mfma_f32_16x16x32_bf16 v[116:119], v[132:135], v[186:189], v[116:119]
	v_mfma_f32_16x16x32_bf16 v[112:115], v[140:143], v[186:189], v[112:115]
	v_mfma_f32_16x16x32_bf16 v[108:111], v[132:135], v[194:197], v[108:111]
	v_mfma_f32_16x16x32_bf16 v[104:107], v[140:143], v[194:197], v[104:107]
	v_mfma_f32_16x16x32_bf16 v[96:99], v[132:135], v[202:205], v[96:99]
	v_mfma_f32_16x16x32_bf16 v[100:103], v[140:143], v[202:205], v[100:103]
	s_setprio 0
	s_setprio 1
	v_mfma_f32_16x16x32_bf16 v[60:63], v[144:147], v[160:163], 0
	v_mfma_f32_16x16x32_bf16 v[56:59], v[152:155], v[160:163], 0
	v_mfma_f32_16x16x32_bf16 v[52:55], v[144:147], v[182:185], 0
	v_mfma_f32_16x16x32_bf16 v[48:51], v[152:155], v[182:185], 0
	v_mfma_f32_16x16x32_bf16 v[44:47], v[144:147], v[190:193], 0
	v_mfma_f32_16x16x32_bf16 v[40:43], v[152:155], v[190:193], 0
	v_mfma_f32_16x16x32_bf16 v[32:35], v[144:147], v[198:201], 0
	v_mfma_f32_16x16x32_bf16 v[36:39], v[152:155], v[198:201], 0
	v_mfma_f32_16x16x32_bf16 v[60:63], v[148:151], v[164:167], v[60:63]
	v_mfma_f32_16x16x32_bf16 v[56:59], v[156:159], v[164:167], v[56:59]
	v_mfma_f32_16x16x32_bf16 v[52:55], v[148:151], v[186:189], v[52:55]
	v_mfma_f32_16x16x32_bf16 v[48:51], v[156:159], v[186:189], v[48:51]
	v_mfma_f32_16x16x32_bf16 v[44:47], v[148:151], v[194:197], v[44:47]
	v_mfma_f32_16x16x32_bf16 v[40:43], v[156:159], v[194:197], v[40:43]
	v_mfma_f32_16x16x32_bf16 v[32:35], v[148:151], v[202:205], v[32:35]
	v_mfma_f32_16x16x32_bf16 v[36:39], v[156:159], v[202:205], v[36:39]
	s_setprio 0
	s_barrier
	s_add_i32 s26, s33, s14
	v_lshl_add_u64 v[216:217], s[4:5], 0, v[170:171]
	s_mov_b32 m0, s26
	ds_read_b128 v[160:163], v211 offset:16384
	ds_read_b128 v[164:167], v211 offset:17408
	ds_read_b128 v[182:185], v211 offset:18432
	ds_read_b128 v[186:189], v211 offset:19456
	ds_read_b128 v[190:193], v211 offset:20480
	ds_read_b128 v[194:197], v211 offset:21504
	ds_read_b128 v[198:201], v211 offset:22528
	ds_read_b128 v[202:205], v211 offset:23552
	global_load_lds_dwordx4 v[216:217], off
	s_add_i32 m0, s26, 0x2000
	s_add_u32 s96, s4, 0x80000
	v_lshl_add_u64 v[218:219], s[4:5], 0, v[174:175]
	s_addc_u32 s97, s5, 0
	s_add_i32 s26, s36, s14
	global_load_lds_dwordx4 v[218:219], off
	v_lshl_add_u64 v[220:221], s[96:97], 0, v[170:171]
	s_mov_b32 m0, s26
	v_lshl_add_u64 v[222:223], s[6:7], 0, v[172:173]
	global_load_lds_dwordx4 v[220:221], off
	v_lshl_add_u64 v[220:221], s[96:97], 0, v[174:175]
	s_add_i32 m0, s26, 0x2000
	s_nop 0
	global_load_lds_dwordx4 v[220:221], off
	v_lshl_add_u64 v[220:221], s[6:7], 0, v[168:169]
	s_mov_b32 m0, s15
	s_nop 0
	global_load_lds_dwordx4 v[220:221], off
	s_mov_b32 m0, s28
	s_nop 0
	global_load_lds_dwordx4 v[222:223], off
	s_waitcnt vmcnt(8) lgkmcnt(0)
	s_barrier
; #define PG8_STAGE(bufoff, gbase, voff) do { _Pragma("unroll") for (int _i = 0; _i < 2; ++_i) \
;         __builtin_amdgcn_global_load_lds((const unsigned*)((const char*)(gbase) + (voff)[_i]), (LAS unsigned*)(lds + (bufoff) + ldsw + _i * 8192), 16, 0, 0); } while (0)
; #define PG8_LDA(dst, b, h) do { _Pragma("unroll") for (int m = 0; m < 4; ++m) _Pragma("unroll") for (int k = 0; k < 2; ++k) dst[m][k] = *(const LAS bf16x8*)(lds + PG8_SA(b, h) + aoff + m * 2048 + k * 1024); } while (0)
; #define PG8_LDB(dst, b, h) do { _Pragma("unroll") for (int n = 0; n < 2; ++n) _Pragma("unroll") for (int k = 0; k < 2; ++k) dst[n][k] = *(const LAS bf16x8*)(lds + PG8_SB(b, h) + boff + n * 2048 + k * 1024); } while (0)
; #define PG8_MMA(ai, bj, At, Bt) do { __builtin_amdgcn_s_setprio(1); _Pragma("unroll") for (int m = 0; m < 4; ++m) _Pragma("unroll") for (int n = 0; n < 2; ++n) _Pragma("unroll") for (int k = 0; k < 2; ++k) \
;         acc[ai][bj][m][n] = __builtin_amdgcn_mfma_f32_16x16x32_bf16(Bt[n][k], At[m][k], acc[ai][bj][m][n], 0, 0, 0); __builtin_amdgcn_s_setprio(0); } while (0)
; #define PG8_WAIT_V(n) asm volatile("s_waitcnt vmcnt(" #n ")" ::: "memory")
; #define PG8_WAIT_L(n) asm volatile("s_waitcnt lgkmcnt(" #n ")" ::: "memory")
; #define PG8_BAR __builtin_amdgcn_s_barrier()
; #define PG8_SCHED __builtin_amdgcn_sched_barrier(0)
; template <class Epi, class Sched>
; __device__ __forceinline__ void gemm_phase(LAS unsigned char* lds, const Gemm g, const Sched& S, const Epi& E) {
;     ...
;             PG8_WAIT_V(8); PG8_WAIT_L(0); PG8_BAR; PG8_MMA(1, 0, At, B0); PG8_MMA(1, 1, At, B1); PG8_BAR; PG8_SCHED;
;             PG8_LDB(B0, 1, 0); PG8_LDB(B1, 1, 1); PG8_SCHED; PG8_LDA(At, 1, 0); PG8_STAGE(PG8_SA(0, 1), a2 + hstepA, voffA);
;             PG8_WAIT_V(8); PG8_WAIT_L(0); PG8_BAR; PG8_MMA(0, 0, At, B0); PG8_MMA(0, 1, At, B1); PG8_BAR; PG8_SCHED;
	s_setprio 1
	v_mfma_f32_16x16x32_bf16 v[92:95], v[128:131], v[160:163], 0
	v_mfma_f32_16x16x32_bf16 v[88:91], v[136:139], v[160:163], 0
	v_mfma_f32_16x16x32_bf16 v[84:87], v[128:131], v[182:185], 0
	v_mfma_f32_16x16x32_bf16 v[80:83], v[136:139], v[182:185], 0
	v_mfma_f32_16x16x32_bf16 v[76:79], v[128:131], v[190:193], 0
	v_mfma_f32_16x16x32_bf16 v[72:75], v[136:139], v[190:193], 0
	v_mfma_f32_16x16x32_bf16 v[64:67], v[128:131], v[198:201], 0
	v_mfma_f32_16x16x32_bf16 v[68:71], v[136:139], v[198:201], 0
	v_mfma_f32_16x16x32_bf16 v[92:95], v[132:135], v[164:167], v[92:95]
	v_mfma_f32_16x16x32_bf16 v[88:91], v[140:143], v[164:167], v[88:91]
	v_mfma_f32_16x16x32_bf16 v[84:87], v[132:135], v[186:189], v[84:87]
	v_mfma_f32_16x16x32_bf16 v[80:83], v[140:143], v[186:189], v[80:83]
	v_mfma_f32_16x16x32_bf16 v[76:79], v[132:135], v[194:197], v[76:79]
	v_mfma_f32_16x16x32_bf16 v[72:75], v[140:143], v[194:197], v[72:75]
	v_mfma_f32_16x16x32_bf16 v[64:67], v[132:135], v[202:205], v[64:67]
	v_mfma_f32_16x16x32_bf16 v[68:71], v[140:143], v[202:205], v[68:71]
	s_setprio 0
	s_setprio 1
	v_mfma_f32_16x16x32_bf16 v[28:31], v[144:147], v[160:163], 0
	v_mfma_f32_16x16x32_bf16 v[24:27], v[152:155], v[160:163], 0
	v_mfma_f32_16x16x32_bf16 v[20:23], v[144:147], v[182:185], 0
	v_mfma_f32_16x16x32_bf16 v[16:19], v[152:155], v[182:185], 0
	v_mfma_f32_16x16x32_bf16 v[12:15], v[144:147], v[190:193], 0
	v_mfma_f32_16x16x32_bf16 v[8:11], v[152:155], v[190:193], 0
	v_mfma_f32_16x16x32_bf16 v[0:3], v[144:147], v[198:201], 0
	v_mfma_f32_16x16x32_bf16 v[4:7], v[152:155], v[198:201], 0
	v_mfma_f32_16x16x32_bf16 v[28:31], v[148:151], v[164:167], v[28:31]
	v_mfma_f32_16x16x32_bf16 v[24:27], v[156:159], v[164:167], v[24:27]
	v_mfma_f32_16x16x32_bf16 v[20:23], v[148:151], v[186:189], v[20:23]
	v_mfma_f32_16x16x32_bf16 v[16:19], v[156:159], v[186:189], v[16:19]
	v_mfma_f32_16x16x32_bf16 v[12:15], v[148:151], v[194:197], v[12:15]
	v_mfma_f32_16x16x32_bf16 v[8:11], v[156:159], v[194:197], v[8:11]
	v_mfma_f32_16x16x32_bf16 v[0:3], v[148:151], v[202:205], v[0:3]
	v_mfma_f32_16x16x32_bf16 v[4:7], v[156:159], v[202:205], v[4:7]
	s_setprio 0
	s_barrier
	s_add_i32 s37, 0, 0x18000
	s_add_i32 s26, 0, 0x1c000
	v_add_u32_e32 v140, s37, v208
	v_add_u32_e32 v156, s26, v208
	ds_read_b128 v[128:131], v140
	ds_read_b128 v[132:135], v140 offset:1024
	ds_read_b128 v[136:139], v140 offset:2048
	ds_read_b128 v[140:143], v140 offset:3072
	ds_read_b128 v[144:147], v156
	ds_read_b128 v[148:151], v156 offset:1024
	ds_read_b128 v[152:155], v156 offset:2048
	ds_read_b128 v[156:159], v156 offset:3072
	s_add_u32 s6, s6, 0x80000
	s_addc_u32 s7, s7, 0
	s_mov_b32 m0, s29
	v_lshl_add_u64 v[224:225], s[6:7], 0, v[168:169]
	ds_read_b128 v[160:163], v211 offset:32768
	ds_read_b128 v[164:167], v211 offset:33792
	ds_read_b128 v[182:185], v211 offset:34816
	ds_read_b128 v[186:189], v211 offset:35840
	ds_read_b128 v[190:193], v211 offset:36864
	ds_read_b128 v[194:197], v211 offset:37888
	ds_read_b128 v[198:201], v211 offset:38912
	ds_read_b128 v[202:205], v211 offset:39936
	global_load_lds_dwordx4 v[224:225], off
	v_lshl_add_u64 v[224:225], s[6:7], 0, v[172:173]
	s_mov_b32 m0, s30
	s_nop 0
	global_load_lds_dwordx4 v[224:225], off
	s_waitcnt vmcnt(8) lgkmcnt(0)
	s_barrier
	s_setprio 1
	v_mfma_f32_16x16x32_bf16 v[124:127], v[128:131], v[160:163], v[124:127]
	v_mfma_f32_16x16x32_bf16 v[120:123], v[136:139], v[160:163], v[120:123]
	v_mfma_f32_16x16x32_bf16 v[116:119], v[128:131], v[182:185], v[116:119]
	v_mfma_f32_16x16x32_bf16 v[112:115], v[136:139], v[182:185], v[112:115]
	v_mfma_f32_16x16x32_bf16 v[108:111], v[128:131], v[190:193], v[108:111]
	v_mfma_f32_16x16x32_bf16 v[104:107], v[136:139], v[190:193], v[104:107]
	v_mfma_f32_16x16x32_bf16 v[96:99], v[128:131], v[198:201], v[96:99]
	v_mfma_f32_16x16x32_bf16 v[100:103], v[136:139], v[198:201], v[100:103]
	v_mfma_f32_16x16x32_bf16 v[124:127], v[132:135], v[164:167], v[124:127]
	v_mfma_f32_16x16x32_bf16 v[120:123], v[140:143], v[164:167], v[120:123]
	v_mfma_f32_16x16x32_bf16 v[116:119], v[132:135], v[186:189], v[116:119]
	v_mfma_f32_16x16x32_bf16 v[112:115], v[140:143], v[186:189], v[112:115]
	v_mfma_f32_16x16x32_bf16 v[108:111], v[132:135], v[194:197], v[108:111]
	v_mfma_f32_16x16x32_bf16 v[104:107], v[140:143], v[194:197], v[104:107]
	v_mfma_f32_16x16x32_bf16 v[96:99], v[132:135], v[202:205], v[96:99]
	v_mfma_f32_16x16x32_bf16 v[100:103], v[140:143], v[202:205], v[100:103]
	s_setprio 0
	s_setprio 1
	v_mfma_f32_16x16x32_bf16 v[60:63], v[144:147], v[160:163], v[60:63]
	v_mfma_f32_16x16x32_bf16 v[56:59], v[152:155], v[160:163], v[56:59]
	v_mfma_f32_16x16x32_bf16 v[52:55], v[144:147], v[182:185], v[52:55]
	v_mfma_f32_16x16x32_bf16 v[48:51], v[152:155], v[182:185], v[48:51]
	v_mfma_f32_16x16x32_bf16 v[44:47], v[144:147], v[190:193], v[44:47]
	v_mfma_f32_16x16x32_bf16 v[40:43], v[152:155], v[190:193], v[40:43]
	v_mfma_f32_16x16x32_bf16 v[32:35], v[144:147], v[198:201], v[32:35]
	v_mfma_f32_16x16x32_bf16 v[36:39], v[152:155], v[198:201], v[36:39]
	v_mfma_f32_16x16x32_bf16 v[60:63], v[148:151], v[164:167], v[60:63]
	v_mfma_f32_16x16x32_bf16 v[56:59], v[156:159], v[164:167], v[56:59]
	v_mfma_f32_16x16x32_bf16 v[52:55], v[148:151], v[186:189], v[52:55]
	v_mfma_f32_16x16x32_bf16 v[48:51], v[156:159], v[186:189], v[48:51]
	v_mfma_f32_16x16x32_bf16 v[44:47], v[148:151], v[194:197], v[44:47]
	v_mfma_f32_16x16x32_bf16 v[40:43], v[156:159], v[194:197], v[40:43]
	v_mfma_f32_16x16x32_bf16 v[32:35], v[148:151], v[202:205], v[32:35]
	v_mfma_f32_16x16x32_bf16 v[36:39], v[156:159], v[202:205], v[36:39]
	s_setprio 0
	s_barrier
; #define PG8_STAGE(bufoff, gbase, voff) do { _Pragma("unroll") for (int _i = 0; _i < 2; ++_i) \
;         __builtin_amdgcn_global_load_lds((const unsigned*)((const char*)(gbase) + (voff)[_i]), (LAS unsigned*)(lds + (bufoff) + ldsw + _i * 8192), 16, 0, 0); } while (0)
; #define PG8_LDA(dst, b, h) do { _Pragma("unroll") for (int m = 0; m < 4; ++m) _Pragma("unroll") for (int k = 0; k < 2; ++k) dst[m][k] = *(const LAS bf16x8*)(lds + PG8_SA(b, h) + aoff + m * 2048 + k * 1024); } while (0)
; #define PG8_MMA(ai, bj, At, Bt) do { __builtin_amdgcn_s_setprio(1); _Pragma("unroll") for (int m = 0; m < 4; ++m) _Pragma("unroll") for (int n = 0; n < 2; ++n) _Pragma("unroll") for (int k = 0; k < 2; ++k) \
;         acc[ai][bj][m][n] = __builtin_amdgcn_mfma_f32_16x16x32_bf16(Bt[n][k], At[m][k], acc[ai][bj][m][n], 0, 0, 0); __builtin_amdgcn_s_setprio(0); } while (0)
; #define PG8_WAIT_V(n) asm volatile("s_waitcnt vmcnt(" #n ")" ::: "memory")
; #define PG8_WAIT_L(n) asm volatile("s_waitcnt lgkmcnt(" #n ")" ::: "memory")
; #define PG8_BAR __builtin_amdgcn_s_barrier()
; #define PG8_SCHED __builtin_amdgcn_sched_barrier(0)
; template <class Epi, class Sched>
; __device__ __forceinline__ void gemm_phase(LAS unsigned char* lds, const Gemm g, const Sched& S, const Epi& E) {
;     ...
;             PG8_LDA(At, 1, 1); PG8_STAGE(PG8_SB(1, 0), b3, voffB); PG8_STAGE(PG8_SB(1, 1), b3 + hstepB, voffB); PG8_STAGE(PG8_SA(1, 0), a3, voffA);
;             PG8_WAIT_V(8); PG8_WAIT_L(0); PG8_BAR; PG8_MMA(1, 0, At, B0); PG8_MMA(1, 1, At, B1); PG8_BAR; PG8_SCHED;
;         }
	s_add_i32 s6, s37, s14
	v_lshl_add_u64 v[216:217], v[216:217], 0, s[80:81]
	s_mov_b32 m0, s6
	ds_read_b128 v[160:163], v211 offset:49152
	ds_read_b128 v[164:167], v211 offset:50176
	ds_read_b128 v[182:185], v211 offset:51200
	ds_read_b128 v[186:189], v211 offset:52224
	ds_read_b128 v[190:193], v211 offset:53248
	ds_read_b128 v[194:197], v211 offset:54272
	ds_read_b128 v[198:201], v211 offset:55296
	ds_read_b128 v[202:205], v211 offset:56320
	global_load_lds_dwordx4 v[216:217], off
	s_add_i32 m0, s6, 0x2000
	s_add_u32 s4, s4, 0x80080
	v_lshl_add_u64 v[216:217], v[218:219], 0, s[80:81]
	s_addc_u32 s5, s5, 0
	s_add_i32 s6, s26, s14
	global_load_lds_dwordx4 v[216:217], off
	v_lshl_add_u64 v[216:217], s[4:5], 0, v[170:171]
	s_mov_b32 m0, s6
	s_nop 0
	global_load_lds_dwordx4 v[216:217], off
	v_lshl_add_u64 v[216:217], s[4:5], 0, v[174:175]
	s_add_i32 m0, s6, 0x2000
	s_nop 0
	global_load_lds_dwordx4 v[216:217], off
	v_lshl_add_u64 v[216:217], v[220:221], 0, s[80:81]
	s_mov_b32 m0, s21
	s_nop 0
	global_load_lds_dwordx4 v[216:217], off
	v_lshl_add_u64 v[216:217], v[222:223], 0, s[80:81]
	s_mov_b32 m0, s18
	s_nop 0
	global_load_lds_dwordx4 v[216:217], off
	s_waitcnt vmcnt(8) lgkmcnt(0)
	s_barrier
	s_setprio 1
	v_mfma_f32_16x16x32_bf16 v[92:95], v[128:131], v[160:163], v[92:95]
	v_mfma_f32_16x16x32_bf16 v[88:91], v[136:139], v[160:163], v[88:91]
	v_mfma_f32_16x16x32_bf16 v[84:87], v[128:131], v[182:185], v[84:87]
	v_mfma_f32_16x16x32_bf16 v[80:83], v[136:139], v[182:185], v[80:83]
	v_mfma_f32_16x16x32_bf16 v[76:79], v[128:131], v[190:193], v[76:79]
	v_mfma_f32_16x16x32_bf16 v[72:75], v[136:139], v[190:193], v[72:75]
	v_mfma_f32_16x16x32_bf16 v[64:67], v[128:131], v[198:201], v[64:67]
	v_mfma_f32_16x16x32_bf16 v[68:71], v[136:139], v[198:201], v[68:71]
	v_mfma_f32_16x16x32_bf16 v[92:95], v[132:135], v[164:167], v[92:95]
	v_mfma_f32_16x16x32_bf16 v[88:91], v[140:143], v[164:167], v[88:91]
	v_mfma_f32_16x16x32_bf16 v[84:87], v[132:135], v[186:189], v[84:87]
	v_mfma_f32_16x16x32_bf16 v[80:83], v[140:143], v[186:189], v[80:83]
	v_mfma_f32_16x16x32_bf16 v[76:79], v[132:135], v[194:197], v[76:79]
	v_mfma_f32_16x16x32_bf16 v[72:75], v[140:143], v[194:197], v[72:75]
	v_mfma_f32_16x16x32_bf16 v[64:67], v[132:135], v[202:205], v[64:67]
	v_mfma_f32_16x16x32_bf16 v[68:71], v[140:143], v[202:205], v[68:71]
	s_setprio 0
	s_setprio 1
	v_mfma_f32_16x16x32_bf16 v[28:31], v[144:147], v[160:163], v[28:31]
	v_mfma_f32_16x16x32_bf16 v[24:27], v[152:155], v[160:163], v[24:27]
	v_mfma_f32_16x16x32_bf16 v[20:23], v[144:147], v[182:185], v[20:23]
	v_mfma_f32_16x16x32_bf16 v[16:19], v[152:155], v[182:185], v[16:19]
	v_mfma_f32_16x16x32_bf16 v[12:15], v[144:147], v[190:193], v[12:15]
	v_mfma_f32_16x16x32_bf16 v[8:11], v[152:155], v[190:193], v[8:11]
	v_mfma_f32_16x16x32_bf16 v[0:3], v[144:147], v[198:201], v[0:3]
	v_mfma_f32_16x16x32_bf16 v[4:7], v[152:155], v[198:201], v[4:7]
	v_mfma_f32_16x16x32_bf16 v[28:31], v[148:151], v[164:167], v[28:31]
	v_mfma_f32_16x16x32_bf16 v[24:27], v[156:159], v[164:167], v[24:27]
	v_mfma_f32_16x16x32_bf16 v[20:23], v[148:151], v[186:189], v[20:23]
	v_mfma_f32_16x16x32_bf16 v[16:19], v[156:159], v[186:189], v[16:19]
	v_mfma_f32_16x16x32_bf16 v[12:15], v[148:151], v[194:197], v[12:15]
	v_mfma_f32_16x16x32_bf16 v[8:11], v[156:159], v[194:197], v[8:11]
	v_mfma_f32_16x16x32_bf16 v[0:3], v[148:151], v[202:205], v[0:3]
	v_mfma_f32_16x16x32_bf16 v[4:7], v[156:159], v[202:205], v[4:7]
	s_setprio 0
	s_barrier
	s_add_i32 s87, s87, 2
	s_add_u32 s0, s0, 0x100
	s_addc_u32 s1, s1, 0
	s_add_u32 s34, s34, 0x100
	s_addc_u32 s35, s35, 0
	s_cmp_gt_u32 s87, 29

;     __device__ bool next(int i, Unit& u) const { if (i >= 2) return false; const int x = c & 7, j = c >> 3; u.pm = 8 * x + (j >> 3) + 4 * i; u.pn = j & 7; return true; }
; #define PG8_STAGE(bufoff, gbase, voff) do { _Pragma("unroll") for (int _i = 0; _i < 2; ++_i) \
;         __builtin_amdgcn_global_load_lds((const unsigned*)((const char*)(gbase) + (voff)[_i]), (LAS unsigned*)(lds + (bufoff) + ldsw + _i * 8192), 16, 0, 0); } while (0)
; #define PG8_LDA(dst, b, h) do { _Pragma("unroll") for (int m = 0; m < 4; ++m) _Pragma("unroll") for (int k = 0; k < 2; ++k) dst[m][k] = *(const LAS bf16x8*)(lds + PG8_SA(b, h) + aoff + m * 2048 + k * 1024); } while (0)
; #define PG8_LDB(dst, b, h) do { _Pragma("unroll") for (int n = 0; n < 2; ++n) _Pragma("unroll") for (int k = 0; k < 2; ++k) dst[n][k] = *(const LAS bf16x8*)(lds + PG8_SB(b, h) + boff + n * 2048 + k * 1024); } while (0)
; #define PG8_WAIT_V(n) asm volatile("s_waitcnt vmcnt(" #n ")" ::: "memory")
; #define PG8_WAIT_L(n) asm volatile("s_waitcnt lgkmcnt(" #n ")" ::: "memory")
; #define PG8_BAR __builtin_amdgcn_s_barrier()
; template <class Epi, class Sched>
; __device__ __forceinline__ void gemm_phase(LAS unsigned char* lds, const Gemm g, const Sched& S, const Epi& E) {
;     ...
;         const bool has_next = S.next(ui + 1, nxt);
;         const char* nA = has_next ? PG8_ABASE(nxt) : cA; const char* nB = has_next ? PG8_BBASE(nxt) : cB;
; #pragma unroll 1
;         for (int t = 0; t < nt; t += 2) {
;             if constexpr (Epi::MIDT >= 0) {
;                 if (t == Epi::MIDT) { int fr_m = fr, fq_m = fq; asm volatile("" : "+v"(fr_m), "+v"(fq_m)); E.mid(acc, cur, wr, wc, fr_m, fq_m); }
;             }
;             const bool last = (t == nt - 2);
;             const char* a1 = cA + (size_t)(t + 1) * kstep;
;             const char* a2 = last ? nA : cA + (size_t)(t + 2) * kstep; const char* b2 = last ? nB : cB + (size_t)(t + 2) * kstep;
;             const char* a3 = a2 + kstep; const char* b3 = b2 + kstep;
;             PG8_LDB(B0, 0, 0); PG8_LDB(B1, 0, 1); PG8_SCHED; PG8_LDA(At, 0, 0); PG8_STAGE(PG8_SA(1, 1), a1 + hstepA, voffA);
;             PG8_WAIT_V(8); PG8_WAIT_L(0); PG8_BAR; PG8_MMA(0, 0, At, B0); PG8_MMA(0, 1, At, B1); PG8_BAR; PG8_SCHED;
;             PG8_LDA(At, 0, 1); PG8_STAGE(PG8_SB(0, 0), b2, voffB); PG8_STAGE(PG8_SB(0, 1), b2 + hstepB, voffB); PG8_STAGE(PG8_SA(0, 0), a2, voffA);
.LBB0_828:
	s_ashr_i32 s39, s38, 31
	s_lshl_b64 s[12:13], s[38:39], 20
	s_add_u32 s52, s50, s12
	s_addc_u32 s53, s51, s13
	s_and_b64 s[12:13], s[0:1], exec
	s_cselect_b32 s12, s53, s61
	s_cselect_b32 s13, s52, s60
	s_ashr_i32 s43, s42, 31
	s_lshl_b64 s[30:31], s[42:43], 20
	s_add_u32 s54, s16, s30
	s_addc_u32 s55, s17, s31
	s_and_b64 s[30:31], s[0:1], exec
	s_cselect_b32 s29, s55, s63
	s_cselect_b32 s30, s54, s62
	s_add_u32 s60, s60, 0x80080
	s_addc_u32 s61, s61, 0
	s_add_u32 s31, s62, 0x100
	s_addc_u32 s34, s63, 0
	s_mov_b32 s35, -2
	s_waitcnt lgkmcnt(0)
	ds_read_b128 v[128:131], v167
	ds_read_b128 v[132:135], v167 offset:1024
	ds_read_b128 v[170:173], v167 offset:2048
	ds_read_b128 v[176:179], v167 offset:3072
	ds_read_b128 v[180:183], v169
	ds_read_b128 v[184:187], v169 offset:1024
	ds_read_b128 v[188:191], v169 offset:2048
	ds_read_b128 v[192:195], v169 offset:3072
	s_add_u32 s39, s60, 0xfff80080
	s_addc_u32 s43, s61, -1
	s_cmp_eq_u32 s35, 28
	s_cselect_b32 s65, s12, s43
	s_cselect_b32 s64, s13, s39
	s_cselect_b32 s63, s29, s34
	s_cselect_b32 s62, s30, s31
	v_lshl_add_u64 v[152:153], s[60:61], 0, v[144:145]
	s_add_i32 m0, s18, 0xc000
	ds_read_b128 v[196:199], v175
	ds_read_b128 v[200:203], v175 offset:1024
	ds_read_b128 v[204:207], v175 offset:2048
	ds_read_b128 v[208:211], v175 offset:3072
	ds_read_b128 v[216:219], v175 offset:4096
	ds_read_b128 v[220:223], v175 offset:5120
	ds_read_b128 v[224:227], v175 offset:6144
	ds_read_b128 v[228:231], v175 offset:7168
	global_load_lds_dwordx4 v[152:153], off
	v_lshl_add_u64 v[152:153], s[60:61], 0, v[146:147]
	s_add_i32 m0, s18, 0xe000
	s_nop 0
	global_load_lds_dwordx4 v[152:153], off
	s_waitcnt vmcnt(8) lgkmcnt(0)
	s_barrier
	s_setprio 1
	v_mfma_f32_16x16x32_bf16 v[124:127], v[128:131], v[196:199], 0
	v_mfma_f32_16x16x32_bf16 v[120:123], v[170:173], v[196:199], 0
	v_mfma_f32_16x16x32_bf16 v[108:111], v[128:131], v[204:207], 0
	v_mfma_f32_16x16x32_bf16 v[104:107], v[170:173], v[204:207], 0
	v_mfma_f32_16x16x32_bf16 v[92:95], v[128:131], v[216:219], 0
	v_mfma_f32_16x16x32_bf16 v[88:91], v[170:173], v[216:219], 0
	v_mfma_f32_16x16x32_bf16 v[76:79], v[128:131], v[224:227], 0
	v_mfma_f32_16x16x32_bf16 v[72:75], v[170:173], v[224:227], 0
	v_mfma_f32_16x16x32_bf16 v[124:127], v[132:135], v[200:203], v[124:127]
	v_mfma_f32_16x16x32_bf16 v[120:123], v[176:179], v[200:203], v[120:123]
	v_mfma_f32_16x16x32_bf16 v[108:111], v[132:135], v[208:211], v[108:111]
	v_mfma_f32_16x16x32_bf16 v[104:107], v[176:179], v[208:211], v[104:107]
	v_mfma_f32_16x16x32_bf16 v[92:95], v[132:135], v[220:223], v[92:95]
	v_mfma_f32_16x16x32_bf16 v[88:91], v[176:179], v[220:223], v[88:91]
	v_mfma_f32_16x16x32_bf16 v[76:79], v[132:135], v[228:231], v[76:79]
	v_mfma_f32_16x16x32_bf16 v[72:75], v[176:179], v[228:231], v[72:75]
	s_setprio 0
	s_setprio 1
	v_mfma_f32_16x16x32_bf16 v[116:119], v[180:183], v[196:199], 0
	v_mfma_f32_16x16x32_bf16 v[112:115], v[188:191], v[196:199], 0
	v_mfma_f32_16x16x32_bf16 v[100:103], v[180:183], v[204:207], 0
	v_mfma_f32_16x16x32_bf16 v[96:99], v[188:191], v[204:207], 0
	v_mfma_f32_16x16x32_bf16 v[84:87], v[180:183], v[216:219], 0
	v_mfma_f32_16x16x32_bf16 v[80:83], v[188:191], v[216:219], 0
	v_mfma_f32_16x16x32_bf16 v[68:71], v[180:183], v[224:227], 0
	v_mfma_f32_16x16x32_bf16 v[64:67], v[188:191], v[224:227], 0
	v_mfma_f32_16x16x32_bf16 v[116:119], v[184:187], v[200:203], v[116:119]
	v_mfma_f32_16x16x32_bf16 v[112:115], v[192:195], v[200:203], v[112:115]
	v_mfma_f32_16x16x32_bf16 v[100:103], v[184:187], v[208:211], v[100:103]
	v_mfma_f32_16x16x32_bf16 v[96:99], v[192:195], v[208:211], v[96:99]
	v_mfma_f32_16x16x32_bf16 v[84:87], v[184:187], v[220:223], v[84:87]
	v_mfma_f32_16x16x32_bf16 v[80:83], v[192:195], v[220:223], v[80:83]
	v_mfma_f32_16x16x32_bf16 v[68:71], v[184:187], v[228:231], v[68:71]
	v_mfma_f32_16x16x32_bf16 v[64:67], v[192:195], v[228:231], v[64:67]
	s_setprio 0
	s_barrier
	s_add_i32 s39, s33, s15
	v_lshl_add_u64 v[152:153], s[62:63], 0, v[138:139]
	s_mov_b32 m0, s39
	ds_read_b128 v[196:199], v175 offset:16384
	ds_read_b128 v[200:203], v175 offset:17408
	ds_read_b128 v[204:207], v175 offset:18432
	ds_read_b128 v[208:211], v175 offset:19456
	ds_read_b128 v[216:219], v175 offset:20480
	ds_read_b128 v[220:223], v175 offset:21504
	ds_read_b128 v[224:227], v175 offset:22528
	ds_read_b128 v[228:231], v175 offset:23552
	global_load_lds_dwordx4 v[152:153], off
	s_add_i32 m0, s39, 0x2000
	s_add_u32 s48, s62, 0x80000
	v_lshl_add_u64 v[156:157], s[62:63], 0, v[142:143]
	s_addc_u32 s49, s63, 0
	s_add_i32 s39, s36, s15
	global_load_lds_dwordx4 v[156:157], off
	v_lshl_add_u64 v[160:161], s[48:49], 0, v[138:139]
	s_mov_b32 m0, s39
	v_lshl_add_u64 v[232:233], s[64:65], 0, v[140:141]
	global_load_lds_dwordx4 v[160:161], off
	v_lshl_add_u64 v[160:161], s[48:49], 0, v[142:143]
	s_add_i32 m0, s39, 0x2000
	s_nop 0
	global_load_lds_dwordx4 v[160:161], off
	v_lshl_add_u64 v[160:161], s[64:65], 0, v[136:137]
	s_mov_b32 m0, s18
	s_nop 0
	global_load_lds_dwordx4 v[160:161], off
	s_mov_b32 m0, s19
	s_nop 0
	global_load_lds_dwordx4 v[232:233], off
	s_waitcnt vmcnt(8) lgkmcnt(0)
	s_barrier
; #define PG8_STAGE(bufoff, gbase, voff) do { _Pragma("unroll") for (int _i = 0; _i < 2; ++_i) \
;         __builtin_amdgcn_global_load_lds((const unsigned*)((const char*)(gbase) + (voff)[_i]), (LAS unsigned*)(lds + (bufoff) + ldsw + _i * 8192), 16, 0, 0); } while (0)
; #define PG8_LDA(dst, b, h) do { _Pragma("unroll") for (int m = 0; m < 4; ++m) _Pragma("unroll") for (int k = 0; k < 2; ++k) dst[m][k] = *(const LAS bf16x8*)(lds + PG8_SA(b, h) + aoff + m * 2048 + k * 1024); } while (0)
; #define PG8_LDB(dst, b, h) do { _Pragma("unroll") for (int n = 0; n < 2; ++n) _Pragma("unroll") for (int k = 0; k < 2; ++k) dst[n][k] = *(const LAS bf16x8*)(lds + PG8_SB(b, h) + boff + n * 2048 + k * 1024); } while (0)
; #define PG8_MMA(ai, bj, At, Bt) do { __builtin_amdgcn_s_setprio(1); _Pragma("unroll") for (int m = 0; m < 4; ++m) _Pragma("unroll") for (int n = 0; n < 2; ++n) _Pragma("unroll") for (int k = 0; k < 2; ++k) \
;         acc[ai][bj][m][n] = __builtin_amdgcn_mfma_f32_16x16x32_bf16(Bt[n][k], At[m][k], acc[ai][bj][m][n], 0, 0, 0); __builtin_amdgcn_s_setprio(0); } while (0)
; #define PG8_WAIT_V(n) asm volatile("s_waitcnt vmcnt(" #n ")" ::: "memory")
; #define PG8_WAIT_L(n) asm volatile("s_waitcnt lgkmcnt(" #n ")" ::: "memory")
; #define PG8_BAR __builtin_amdgcn_s_barrier()
; #define PG8_SCHED __builtin_amdgcn_sched_barrier(0)
; template <class Epi, class Sched>
; __device__ __forceinline__ void gemm_phase(LAS unsigned char* lds, const Gemm g, const Sched& S, const Epi& E) {
;     ...
;             PG8_WAIT_V(8); PG8_WAIT_L(0); PG8_BAR; PG8_MMA(1, 0, At, B0); PG8_MMA(1, 1, At, B1); PG8_BAR; PG8_SCHED;
;             PG8_LDB(B0, 1, 0); PG8_LDB(B1, 1, 1); PG8_SCHED; PG8_LDA(At, 1, 0); PG8_STAGE(PG8_SA(0, 1), a2 + hstepA, voffA);
;             PG8_WAIT_V(8); PG8_WAIT_L(0); PG8_BAR; PG8_MMA(0, 0, At, B0); PG8_MMA(0, 1, At, B1); PG8_BAR; PG8_SCHED;
	s_setprio 1
	v_mfma_f32_16x16x32_bf16 v[60:63], v[128:131], v[196:199], 0
	v_mfma_f32_16x16x32_bf16 v[56:59], v[170:173], v[196:199], 0
	v_mfma_f32_16x16x32_bf16 v[44:47], v[128:131], v[204:207], 0
	v_mfma_f32_16x16x32_bf16 v[40:43], v[170:173], v[204:207], 0
	v_mfma_f32_16x16x32_bf16 v[28:31], v[128:131], v[216:219], 0
	v_mfma_f32_16x16x32_bf16 v[24:27], v[170:173], v[216:219], 0
	v_mfma_f32_16x16x32_bf16 v[12:15], v[128:131], v[224:227], 0
	v_mfma_f32_16x16x32_bf16 v[8:11], v[170:173], v[224:227], 0
	v_mfma_f32_16x16x32_bf16 v[60:63], v[132:135], v[200:203], v[60:63]
	v_mfma_f32_16x16x32_bf16 v[56:59], v[176:179], v[200:203], v[56:59]
	v_mfma_f32_16x16x32_bf16 v[44:47], v[132:135], v[208:211], v[44:47]
	v_mfma_f32_16x16x32_bf16 v[40:43], v[176:179], v[208:211], v[40:43]
	v_mfma_f32_16x16x32_bf16 v[28:31], v[132:135], v[220:223], v[28:31]
	v_mfma_f32_16x16x32_bf16 v[24:27], v[176:179], v[220:223], v[24:27]
	v_mfma_f32_16x16x32_bf16 v[12:15], v[132:135], v[228:231], v[12:15]
	v_mfma_f32_16x16x32_bf16 v[8:11], v[176:179], v[228:231], v[8:11]
	s_setprio 0
	s_setprio 1
	v_mfma_f32_16x16x32_bf16 v[52:55], v[180:183], v[196:199], 0
	v_mfma_f32_16x16x32_bf16 v[48:51], v[188:191], v[196:199], 0
	v_mfma_f32_16x16x32_bf16 v[36:39], v[180:183], v[204:207], 0
	v_mfma_f32_16x16x32_bf16 v[32:35], v[188:191], v[204:207], 0
	v_mfma_f32_16x16x32_bf16 v[20:23], v[180:183], v[216:219], 0
	v_mfma_f32_16x16x32_bf16 v[16:19], v[188:191], v[216:219], 0
	v_mfma_f32_16x16x32_bf16 v[4:7], v[180:183], v[224:227], 0
	v_mfma_f32_16x16x32_bf16 v[0:3], v[188:191], v[224:227], 0
	v_mfma_f32_16x16x32_bf16 v[52:55], v[184:187], v[200:203], v[52:55]
	v_mfma_f32_16x16x32_bf16 v[48:51], v[192:195], v[200:203], v[48:51]
	v_mfma_f32_16x16x32_bf16 v[36:39], v[184:187], v[208:211], v[36:39]
	v_mfma_f32_16x16x32_bf16 v[32:35], v[192:195], v[208:211], v[32:35]
	v_mfma_f32_16x16x32_bf16 v[20:23], v[184:187], v[220:223], v[20:23]
	v_mfma_f32_16x16x32_bf16 v[16:19], v[192:195], v[220:223], v[16:19]
	v_mfma_f32_16x16x32_bf16 v[4:7], v[184:187], v[228:231], v[4:7]
	v_mfma_f32_16x16x32_bf16 v[0:3], v[192:195], v[228:231], v[0:3]
	s_setprio 0
	s_barrier
	v_add_u32_e32 v154, s37, v165
	ds_read_b128 v[128:131], v154
	ds_read_b128 v[132:135], v154 offset:1024
	ds_read_b128 v[170:173], v154 offset:2048
	ds_read_b128 v[176:179], v154 offset:3072
	v_add_u32_e32 v154, s26, v165
	ds_read_b128 v[180:183], v154
	ds_read_b128 v[184:187], v154 offset:1024
	ds_read_b128 v[188:191], v154 offset:2048
	ds_read_b128 v[192:195], v154 offset:3072
	s_add_u32 s48, s64, 0x80000
	s_addc_u32 s49, s65, 0
	s_mov_b32 m0, s21
	v_lshl_add_u64 v[234:235], s[48:49], 0, v[136:137]
	ds_read_b128 v[196:199], v175 offset:32768
	ds_read_b128 v[200:203], v175 offset:33792
	ds_read_b128 v[204:207], v175 offset:34816
	ds_read_b128 v[208:211], v175 offset:35840
	ds_read_b128 v[216:219], v175 offset:36864
	ds_read_b128 v[220:223], v175 offset:37888
	ds_read_b128 v[224:227], v175 offset:38912
	ds_read_b128 v[228:231], v175 offset:39936
	global_load_lds_dwordx4 v[234:235], off
	v_lshl_add_u64 v[234:235], s[48:49], 0, v[140:141]
	s_mov_b32 m0, s22
	s_nop 0
	global_load_lds_dwordx4 v[234:235], off
	s_waitcnt vmcnt(8) lgkmcnt(0)
	s_barrier
	s_setprio 1
	v_mfma_f32_16x16x32_bf16 v[124:127], v[128:131], v[196:199], v[124:127]
	v_mfma_f32_16x16x32_bf16 v[120:123], v[170:173], v[196:199], v[120:123]
	v_mfma_f32_16x16x32_bf16 v[108:111], v[128:131], v[204:207], v[108:111]
	v_mfma_f32_16x16x32_bf16 v[104:107], v[170:173], v[204:207], v[104:107]
	v_mfma_f32_16x16x32_bf16 v[92:95], v[128:131], v[216:219], v[92:95]
	v_mfma_f32_16x16x32_bf16 v[88:91], v[170:173], v[216:219], v[88:91]
	v_mfma_f32_16x16x32_bf16 v[76:79], v[128:131], v[224:227], v[76:79]
	v_mfma_f32_16x16x32_bf16 v[72:75], v[170:173], v[224:227], v[72:75]
	v_mfma_f32_16x16x32_bf16 v[124:127], v[132:135], v[200:203], v[124:127]
	v_mfma_f32_16x16x32_bf16 v[120:123], v[176:179], v[200:203], v[120:123]
	v_mfma_f32_16x16x32_bf16 v[108:111], v[132:135], v[208:211], v[108:111]
	v_mfma_f32_16x16x32_bf16 v[104:107], v[176:179], v[208:211], v[104:107]
	v_mfma_f32_16x16x32_bf16 v[92:95], v[132:135], v[220:223], v[92:95]
	v_mfma_f32_16x16x32_bf16 v[88:91], v[176:179], v[220:223], v[88:91]
	v_mfma_f32_16x16x32_bf16 v[76:79], v[132:135], v[228:231], v[76:79]
	v_mfma_f32_16x16x32_bf16 v[72:75], v[176:179], v[228:231], v[72:75]
	s_setprio 0
	s_setprio 1
	v_mfma_f32_16x16x32_bf16 v[116:119], v[180:183], v[196:199], v[116:119]
	v_mfma_f32_16x16x32_bf16 v[112:115], v[188:191], v[196:199], v[112:115]
	v_mfma_f32_16x16x32_bf16 v[100:103], v[180:183], v[204:207], v[100:103]
	v_mfma_f32_16x16x32_bf16 v[96:99], v[188:191], v[204:207], v[96:99]
	v_mfma_f32_16x16x32_bf16 v[84:87], v[180:183], v[216:219], v[84:87]
	v_mfma_f32_16x16x32_bf16 v[80:83], v[188:191], v[216:219], v[80:83]
	v_mfma_f32_16x16x32_bf16 v[68:71], v[180:183], v[224:227], v[68:71]
	v_mfma_f32_16x16x32_bf16 v[64:67], v[188:191], v[224:227], v[64:67]
	v_mfma_f32_16x16x32_bf16 v[116:119], v[184:187], v[200:203], v[116:119]
	v_mfma_f32_16x16x32_bf16 v[112:115], v[192:195], v[200:203], v[112:115]
	v_mfma_f32_16x16x32_bf16 v[100:103], v[184:187], v[208:211], v[100:103]
	v_mfma_f32_16x16x32_bf16 v[96:99], v[192:195], v[208:211], v[96:99]
	v_mfma_f32_16x16x32_bf16 v[84:87], v[184:187], v[220:223], v[84:87]
	v_mfma_f32_16x16x32_bf16 v[80:83], v[192:195], v[220:223], v[80:83]
	v_mfma_f32_16x16x32_bf16 v[68:71], v[184:187], v[228:231], v[68:71]
	v_mfma_f32_16x16x32_bf16 v[64:67], v[192:195], v[228:231], v[64:67]
	s_setprio 0
	s_barrier
; #define PG8_STAGE(bufoff, gbase, voff) do { _Pragma("unroll") for (int _i = 0; _i < 2; ++_i) \
;         __builtin_amdgcn_global_load_lds((const unsigned*)((const char*)(gbase) + (voff)[_i]), (LAS unsigned*)(lds + (bufoff) + ldsw + _i * 8192), 16, 0, 0); } while (0)
; #define PG8_LDA(dst, b, h) do { _Pragma("unroll") for (int m = 0; m < 4; ++m) _Pragma("unroll") for (int k = 0; k < 2; ++k) dst[m][k] = *(const LAS bf16x8*)(lds + PG8_SA(b, h) + aoff + m * 2048 + k * 1024); } while (0)
; #define PG8_MMA(ai, bj, At, Bt) do { __builtin_amdgcn_s_setprio(1); _Pragma("unroll") for (int m = 0; m < 4; ++m) _Pragma("unroll") for (int n = 0; n < 2; ++n) _Pragma("unroll") for (int k = 0; k < 2; ++k) \
;         acc[ai][bj][m][n] = __builtin_amdgcn_mfma_f32_16x16x32_bf16(Bt[n][k], At[m][k], acc[ai][bj][m][n], 0, 0, 0); __builtin_amdgcn_s_setprio(0); } while (0)
; #define PG8_WAIT_V(n) asm volatile("s_waitcnt vmcnt(" #n ")" ::: "memory")
; #define PG8_WAIT_L(n) asm volatile("s_waitcnt lgkmcnt(" #n ")" ::: "memory")
; #define PG8_BAR __builtin_amdgcn_s_barrier()
; #define PG8_SCHED __builtin_amdgcn_sched_barrier(0)
; template <class Epi, class Sched>
; __device__ __forceinline__ void gemm_phase(LAS unsigned char* lds, const Gemm g, const Sched& S, const Epi& E) {
;     ...
;             PG8_LDA(At, 1, 1); PG8_STAGE(PG8_SB(1, 0), b3, voffB); PG8_STAGE(PG8_SB(1, 1), b3 + hstepB, voffB); PG8_STAGE(PG8_SA(1, 0), a3, voffA);
;             PG8_WAIT_V(8); PG8_WAIT_L(0); PG8_BAR; PG8_MMA(1, 0, At, B0); PG8_MMA(1, 1, At, B1); PG8_BAR; PG8_SCHED;
;         }
	s_add_i32 s39, s37, s15
	v_lshl_add_u64 v[152:153], v[152:153], 0, s[8:9]
	s_mov_b32 m0, s39
	ds_read_b128 v[196:199], v175 offset:49152
	ds_read_b128 v[200:203], v175 offset:50176
	ds_read_b128 v[204:207], v175 offset:51200
	ds_read_b128 v[208:211], v175 offset:52224
	ds_read_b128 v[216:219], v175 offset:53248
	ds_read_b128 v[220:223], v175 offset:54272
	ds_read_b128 v[224:227], v175 offset:55296
	ds_read_b128 v[228:231], v175 offset:56320
	global_load_lds_dwordx4 v[152:153], off
	s_add_i32 m0, s39, 0x2000
	s_add_u32 s48, s62, 0x80080
	v_lshl_add_u64 v[152:153], v[156:157], 0, s[8:9]
	s_addc_u32 s49, s63, 0
	s_add_i32 s39, s26, s15
	global_load_lds_dwordx4 v[152:153], off
	v_lshl_add_u64 v[152:153], s[48:49], 0, v[138:139]
	s_mov_b32 m0, s39
	s_nop 0
	global_load_lds_dwordx4 v[152:153], off
	v_lshl_add_u64 v[152:153], s[48:49], 0, v[142:143]
	s_add_i32 m0, s39, 0x2000
	s_nop 0
	global_load_lds_dwordx4 v[152:153], off
	v_lshl_add_u64 v[152:153], v[160:161], 0, s[8:9]
	s_mov_b32 m0, s25
	s_nop 0
	global_load_lds_dwordx4 v[152:153], off
	v_lshl_add_u64 v[152:153], v[232:233], 0, s[8:9]
	s_mov_b32 m0, s27
	s_nop 0
	global_load_lds_dwordx4 v[152:153], off
	s_waitcnt vmcnt(8) lgkmcnt(0)
	s_barrier
	s_setprio 1
	v_mfma_f32_16x16x32_bf16 v[60:63], v[128:131], v[196:199], v[60:63]
	v_mfma_f32_16x16x32_bf16 v[56:59], v[170:173], v[196:199], v[56:59]
	v_mfma_f32_16x16x32_bf16 v[44:47], v[128:131], v[204:207], v[44:47]
	v_mfma_f32_16x16x32_bf16 v[40:43], v[170:173], v[204:207], v[40:43]
	v_mfma_f32_16x16x32_bf16 v[28:31], v[128:131], v[216:219], v[28:31]
	v_mfma_f32_16x16x32_bf16 v[24:27], v[170:173], v[216:219], v[24:27]
	v_mfma_f32_16x16x32_bf16 v[12:15], v[128:131], v[224:227], v[12:15]
	v_mfma_f32_16x16x32_bf16 v[8:11], v[170:173], v[224:227], v[8:11]
	v_mfma_f32_16x16x32_bf16 v[60:63], v[132:135], v[200:203], v[60:63]
	v_mfma_f32_16x16x32_bf16 v[56:59], v[176:179], v[200:203], v[56:59]
	v_mfma_f32_16x16x32_bf16 v[44:47], v[132:135], v[208:211], v[44:47]
	v_mfma_f32_16x16x32_bf16 v[40:43], v[176:179], v[208:211], v[40:43]
	v_mfma_f32_16x16x32_bf16 v[28:31], v[132:135], v[220:223], v[28:31]
	v_mfma_f32_16x16x32_bf16 v[24:27], v[176:179], v[220:223], v[24:27]
	v_mfma_f32_16x16x32_bf16 v[12:15], v[132:135], v[228:231], v[12:15]
	v_mfma_f32_16x16x32_bf16 v[8:11], v[176:179], v[228:231], v[8:11]
	s_setprio 0
	s_setprio 1
	v_mfma_f32_16x16x32_bf16 v[52:55], v[180:183], v[196:199], v[52:55]
	v_mfma_f32_16x16x32_bf16 v[48:51], v[188:191], v[196:199], v[48:51]
	v_mfma_f32_16x16x32_bf16 v[36:39], v[180:183], v[204:207], v[36:39]
	v_mfma_f32_16x16x32_bf16 v[32:35], v[188:191], v[204:207], v[32:35]
	v_mfma_f32_16x16x32_bf16 v[20:23], v[180:183], v[216:219], v[20:23]
	v_mfma_f32_16x16x32_bf16 v[16:19], v[188:191], v[216:219], v[16:19]
	v_mfma_f32_16x16x32_bf16 v[4:7], v[180:183], v[224:227], v[4:7]
	v_mfma_f32_16x16x32_bf16 v[0:3], v[188:191], v[224:227], v[0:3]
	v_mfma_f32_16x16x32_bf16 v[52:55], v[184:187], v[200:203], v[52:55]
	v_mfma_f32_16x16x32_bf16 v[48:51], v[192:195], v[200:203], v[48:51]
	v_mfma_f32_16x16x32_bf16 v[36:39], v[184:187], v[208:211], v[36:39]
	v_mfma_f32_16x16x32_bf16 v[32:35], v[192:195], v[208:211], v[32:35]
	v_mfma_f32_16x16x32_bf16 v[20:23], v[184:187], v[220:223], v[20:23]
	v_mfma_f32_16x16x32_bf16 v[16:19], v[192:195], v[220:223], v[16:19]
	v_mfma_f32_16x16x32_bf16 v[4:7], v[184:187], v[228:231], v[4:7]
	v_mfma_f32_16x16x32_bf16 v[0:3], v[192:195], v[228:231], v[0:3]
	s_setprio 0
	s_barrier
	s_add_i32 s35, s35, 2
	s_add_u32 s60, s60, 0x100
	s_addc_u32 s61, s61, 0
	s_add_u32 s31, s31, 0x100
	s_addc_u32 s34, s34, 0
	s_cmp_gt_u32 s35, 29

;     __device__ bool next(int i, Unit& u) const { if (i >= 2) return false; const int x = c & 7, j = c >> 3; u.pm = 8 * x + (j >> 3) + 4 * i; u.pn = j & 7; return true; }
; #define PG8_STAGE(bufoff, gbase, voff) do { _Pragma("unroll") for (int _i = 0; _i < 2; ++_i) \
;         __builtin_amdgcn_global_load_lds((const unsigned*)((const char*)(gbase) + (voff)[_i]), (LAS unsigned*)(lds + (bufoff) + ldsw + _i * 8192), 16, 0, 0); } while (0)
; #define PG8_LDA(dst, b, h) do { _Pragma("unroll") for (int m = 0; m < 4; ++m) _Pragma("unroll") for (int k = 0; k < 2; ++k) dst[m][k] = *(const LAS bf16x8*)(lds + PG8_SA(b, h) + aoff + m * 2048 + k * 1024); } while (0)
; #define PG8_LDB(dst, b, h) do { _Pragma("unroll") for (int n = 0; n < 2; ++n) _Pragma("unroll") for (int k = 0; k < 2; ++k) dst[n][k] = *(const LAS bf16x8*)(lds + PG8_SB(b, h) + boff + n * 2048 + k * 1024); } while (0)
; #define PG8_WAIT_V(n) asm volatile("s_waitcnt vmcnt(" #n ")" ::: "memory")
; #define PG8_WAIT_L(n) asm volatile("s_waitcnt lgkmcnt(" #n ")" ::: "memory")
; #define PG8_BAR __builtin_amdgcn_s_barrier()
; template <class Epi, class Sched>
; __device__ __forceinline__ void gemm_phase(LAS unsigned char* lds, const Gemm g, const Sched& S, const Epi& E) {
;     ...
;         const bool has_next = S.next(ui + 1, nxt);
;         const char* nA = has_next ? PG8_ABASE(nxt) : cA; const char* nB = has_next ? PG8_BBASE(nxt) : cB;
; #pragma unroll 1
;         for (int t = 0; t < nt; t += 2) {
;             if constexpr (Epi::MIDT >= 0) {
;                 if (t == Epi::MIDT) { int fr_m = fr, fq_m = fq; asm volatile("" : "+v"(fr_m), "+v"(fq_m)); E.mid(acc, cur, wr, wc, fr_m, fq_m); }
;             }
;             const bool last = (t == nt - 2);
;             const char* a1 = cA + (size_t)(t + 1) * kstep;
;             const char* a2 = last ? nA : cA + (size_t)(t + 2) * kstep; const char* b2 = last ? nB : cB + (size_t)(t + 2) * kstep;
;             const char* a3 = a2 + kstep; const char* b3 = b2 + kstep;
;             PG8_LDB(B0, 0, 0); PG8_LDB(B1, 0, 1); PG8_SCHED; PG8_LDA(At, 0, 0); PG8_STAGE(PG8_SA(1, 1), a1 + hstepA, voffA);
;             PG8_WAIT_V(8); PG8_WAIT_L(0); PG8_BAR; PG8_MMA(0, 0, At, B0); PG8_MMA(0, 1, At, B1); PG8_BAR; PG8_SCHED;
;             PG8_LDA(At, 0, 1); PG8_STAGE(PG8_SB(0, 0), b2, voffB); PG8_STAGE(PG8_SB(0, 1), b2 + hstepB, voffB); PG8_STAGE(PG8_SA(0, 0), a2, voffA);
.LBB0_922:
	s_ashr_i32 s53, s52, 31
	s_lshl_b64 s[12:13], s[52:53], 20
	s_add_u32 s56, s74, s12
	s_addc_u32 s57, s75, s13
	s_and_b64 s[12:13], s[6:7], exec
	s_cselect_b32 s12, s57, s1
	s_cselect_b32 s13, s56, s0
	s_ashr_i32 s55, s54, 31
	s_lshl_b64 s[58:59], s[54:55], 20
	s_add_u32 s58, s46, s58
	s_addc_u32 s59, s47, s59
	s_and_b64 s[6:7], s[6:7], exec
	s_cselect_b32 s53, s59, s5
	s_cselect_b32 s55, s58, s4
	s_add_u32 s0, s0, 0x80080
	s_addc_u32 s1, s1, 0
	s_add_u32 s60, s4, 0x100
	s_addc_u32 s61, s5, 0
	s_mov_b32 s62, -2
	ds_read_b128 v[64:67], v209
	ds_read_b128 v[68:71], v209 offset:1024
	ds_read_b128 v[72:75], v209 offset:2048
	ds_read_b128 v[76:79], v209 offset:3072
	ds_read_b128 v[84:87], v210
	ds_read_b128 v[88:91], v210 offset:1024
	ds_read_b128 v[92:95], v210 offset:2048
	ds_read_b128 v[96:99], v210 offset:3072
	s_add_u32 s4, s0, 0xfff80080
	s_addc_u32 s5, s1, -1
	s_cmp_eq_u32 s62, 28
	s_cselect_b32 s7, s12, s5
	s_cselect_b32 s6, s13, s4
	s_cselect_b32 s5, s53, s61
	s_cselect_b32 s4, s55, s60
	v_lshl_add_u64 v[218:219], s[0:1], 0, v[170:171]
	s_add_i32 m0, s15, 0xc000
	ds_read_b128 v[174:177], v211
	ds_read_b128 v[178:181], v211 offset:1024
	ds_read_b128 v[182:185], v211 offset:2048
	ds_read_b128 v[186:189], v211 offset:3072
	ds_read_b128 v[190:193], v211 offset:4096
	ds_read_b128 v[194:197], v211 offset:5120
	ds_read_b128 v[198:201], v211 offset:6144
	ds_read_b128 v[202:205], v211 offset:7168
	global_load_lds_dwordx4 v[218:219], off
	v_lshl_add_u64 v[218:219], s[0:1], 0, v[172:173]
	s_add_i32 m0, s15, 0xe000
	s_nop 0
	global_load_lds_dwordx4 v[218:219], off
	s_waitcnt vmcnt(8) lgkmcnt(0)
	s_barrier
	s_setprio 1
	v_mfma_f32_16x16x32_bf16 v[156:159], v[64:67], v[174:177], 0
	v_mfma_f32_16x16x32_bf16 v[148:151], v[72:75], v[174:177], 0
	v_mfma_f32_16x16x32_bf16 v[140:143], v[64:67], v[182:185], 0
	v_mfma_f32_16x16x32_bf16 v[136:139], v[72:75], v[182:185], 0
	v_mfma_f32_16x16x32_bf16 v[124:127], v[64:67], v[190:193], 0
	v_mfma_f32_16x16x32_bf16 v[120:123], v[72:75], v[190:193], 0
	v_mfma_f32_16x16x32_bf16 v[108:111], v[64:67], v[198:201], 0
	v_mfma_f32_16x16x32_bf16 v[104:107], v[72:75], v[198:201], 0
	v_mfma_f32_16x16x32_bf16 v[156:159], v[68:71], v[178:181], v[156:159]
	v_mfma_f32_16x16x32_bf16 v[148:151], v[76:79], v[178:181], v[148:151]
	v_mfma_f32_16x16x32_bf16 v[140:143], v[68:71], v[186:189], v[140:143]
	v_mfma_f32_16x16x32_bf16 v[136:139], v[76:79], v[186:189], v[136:139]
	v_mfma_f32_16x16x32_bf16 v[124:127], v[68:71], v[194:197], v[124:127]
	v_mfma_f32_16x16x32_bf16 v[120:123], v[76:79], v[194:197], v[120:123]
	v_mfma_f32_16x16x32_bf16 v[108:111], v[68:71], v[202:205], v[108:111]
	v_mfma_f32_16x16x32_bf16 v[104:107], v[76:79], v[202:205], v[104:107]
	s_setprio 0
	s_setprio 1
	v_mfma_f32_16x16x32_bf16 v[152:155], v[84:87], v[174:177], 0
	v_mfma_f32_16x16x32_bf16 v[144:147], v[92:95], v[174:177], 0
	v_mfma_f32_16x16x32_bf16 v[132:135], v[84:87], v[182:185], 0
	v_mfma_f32_16x16x32_bf16 v[128:131], v[92:95], v[182:185], 0
	v_mfma_f32_16x16x32_bf16 v[116:119], v[84:87], v[190:193], 0
	v_mfma_f32_16x16x32_bf16 v[112:115], v[92:95], v[190:193], 0
	v_mfma_f32_16x16x32_bf16 v[80:83], v[84:87], v[198:201], 0
	v_mfma_f32_16x16x32_bf16 v[100:103], v[92:95], v[198:201], 0
	v_mfma_f32_16x16x32_bf16 v[152:155], v[88:91], v[178:181], v[152:155]
	v_mfma_f32_16x16x32_bf16 v[144:147], v[96:99], v[178:181], v[144:147]
	v_mfma_f32_16x16x32_bf16 v[132:135], v[88:91], v[186:189], v[132:135]
	v_mfma_f32_16x16x32_bf16 v[128:131], v[96:99], v[186:189], v[128:131]
	v_mfma_f32_16x16x32_bf16 v[116:119], v[88:91], v[194:197], v[116:119]
	v_mfma_f32_16x16x32_bf16 v[112:115], v[96:99], v[194:197], v[112:115]
	v_mfma_f32_16x16x32_bf16 v[80:83], v[88:91], v[202:205], v[80:83]
	v_mfma_f32_16x16x32_bf16 v[100:103], v[96:99], v[202:205], v[100:103]
	s_setprio 0
	s_barrier
	s_add_i32 s63, s33, s14
	v_lshl_add_u64 v[218:219], s[4:5], 0, v[162:163]
	s_mov_b32 m0, s63
	ds_read_b128 v[174:177], v211 offset:16384
	ds_read_b128 v[178:181], v211 offset:17408
	ds_read_b128 v[182:185], v211 offset:18432
	ds_read_b128 v[186:189], v211 offset:19456
	ds_read_b128 v[190:193], v211 offset:20480
	ds_read_b128 v[194:197], v211 offset:21504
	ds_read_b128 v[198:201], v211 offset:22528
	ds_read_b128 v[202:205], v211 offset:23552
	global_load_lds_dwordx4 v[218:219], off
	s_add_i32 m0, s63, 0x2000
	s_add_u32 s70, s4, 0x80000
	v_lshl_add_u64 v[220:221], s[4:5], 0, v[166:167]
	s_addc_u32 s71, s5, 0
	s_add_i32 s63, s36, s14
	global_load_lds_dwordx4 v[220:221], off
	v_lshl_add_u64 v[222:223], s[70:71], 0, v[162:163]
	s_mov_b32 m0, s63
	v_lshl_add_u64 v[224:225], s[6:7], 0, v[164:165]
	global_load_lds_dwordx4 v[222:223], off
	v_lshl_add_u64 v[222:223], s[70:71], 0, v[166:167]
	s_add_i32 m0, s63, 0x2000
	s_nop 0
	global_load_lds_dwordx4 v[222:223], off
	v_lshl_add_u64 v[222:223], s[6:7], 0, v[160:161]
	s_mov_b32 m0, s15
	s_nop 0
	global_load_lds_dwordx4 v[222:223], off
	s_mov_b32 m0, s21
	s_nop 0
	global_load_lds_dwordx4 v[224:225], off
	s_waitcnt vmcnt(8) lgkmcnt(0)
	s_barrier
; #define PG8_STAGE(bufoff, gbase, voff) do { _Pragma("unroll") for (int _i = 0; _i < 2; ++_i) \
;         __builtin_amdgcn_global_load_lds((const unsigned*)((const char*)(gbase) + (voff)[_i]), (LAS unsigned*)(lds + (bufoff) + ldsw + _i * 8192), 16, 0, 0); } while (0)
; #define PG8_LDA(dst, b, h) do { _Pragma("unroll") for (int m = 0; m < 4; ++m) _Pragma("unroll") for (int k = 0; k < 2; ++k) dst[m][k] = *(const LAS bf16x8*)(lds + PG8_SA(b, h) + aoff + m * 2048 + k * 1024); } while (0)
; #define PG8_LDB(dst, b, h) do { _Pragma("unroll") for (int n = 0; n < 2; ++n) _Pragma("unroll") for (int k = 0; k < 2; ++k) dst[n][k] = *(const LAS bf16x8*)(lds + PG8_SB(b, h) + boff + n * 2048 + k * 1024); } while (0)
; #define PG8_MMA(ai, bj, At, Bt) do { __builtin_amdgcn_s_setprio(1); _Pragma("unroll") for (int m = 0; m < 4; ++m) _Pragma("unroll") for (int n = 0; n < 2; ++n) _Pragma("unroll") for (int k = 0; k < 2; ++k) \
;         acc[ai][bj][m][n] = __builtin_amdgcn_mfma_f32_16x16x32_bf16(Bt[n][k], At[m][k], acc[ai][bj][m][n], 0, 0, 0); __builtin_amdgcn_s_setprio(0); } while (0)
; #define PG8_WAIT_V(n) asm volatile("s_waitcnt vmcnt(" #n ")" ::: "memory")
; #define PG8_WAIT_L(n) asm volatile("s_waitcnt lgkmcnt(" #n ")" ::: "memory")
; #define PG8_BAR __builtin_amdgcn_s_barrier()
; #define PG8_SCHED __builtin_amdgcn_sched_barrier(0)
; template <class Epi, class Sched>
; __device__ __forceinline__ void gemm_phase(LAS unsigned char* lds, const Gemm g, const Sched& S, const Epi& E) {
;     ...
;             PG8_WAIT_V(8); PG8_WAIT_L(0); PG8_BAR; PG8_MMA(1, 0, At, B0); PG8_MMA(1, 1, At, B1); PG8_BAR; PG8_SCHED;
;             PG8_LDB(B0, 1, 0); PG8_LDB(B1, 1, 1); PG8_SCHED; PG8_LDA(At, 1, 0); PG8_STAGE(PG8_SA(0, 1), a2 + hstepA, voffA);
;             PG8_WAIT_V(8); PG8_WAIT_L(0); PG8_BAR; PG8_MMA(0, 0, At, B0); PG8_MMA(0, 1, At, B1); PG8_BAR; PG8_SCHED;
	s_setprio 1
	v_mfma_f32_16x16x32_bf16 v[60:63], v[64:67], v[174:177], 0
	v_mfma_f32_16x16x32_bf16 v[56:59], v[72:75], v[174:177], 0
	v_mfma_f32_16x16x32_bf16 v[44:47], v[64:67], v[182:185], 0
	v_mfma_f32_16x16x32_bf16 v[40:43], v[72:75], v[182:185], 0
	v_mfma_f32_16x16x32_bf16 v[28:31], v[64:67], v[190:193], 0
	v_mfma_f32_16x16x32_bf16 v[24:27], v[72:75], v[190:193], 0
	v_mfma_f32_16x16x32_bf16 v[12:15], v[64:67], v[198:201], 0
	v_mfma_f32_16x16x32_bf16 v[8:11], v[72:75], v[198:201], 0
	v_mfma_f32_16x16x32_bf16 v[60:63], v[68:71], v[178:181], v[60:63]
	v_mfma_f32_16x16x32_bf16 v[56:59], v[76:79], v[178:181], v[56:59]
	v_mfma_f32_16x16x32_bf16 v[44:47], v[68:71], v[186:189], v[44:47]
	v_mfma_f32_16x16x32_bf16 v[40:43], v[76:79], v[186:189], v[40:43]
	v_mfma_f32_16x16x32_bf16 v[28:31], v[68:71], v[194:197], v[28:31]
	v_mfma_f32_16x16x32_bf16 v[24:27], v[76:79], v[194:197], v[24:27]
	v_mfma_f32_16x16x32_bf16 v[12:15], v[68:71], v[202:205], v[12:15]
	v_mfma_f32_16x16x32_bf16 v[8:11], v[76:79], v[202:205], v[8:11]
	s_setprio 0
	s_setprio 1
	v_mfma_f32_16x16x32_bf16 v[52:55], v[84:87], v[174:177], 0
	v_mfma_f32_16x16x32_bf16 v[48:51], v[92:95], v[174:177], 0
	v_mfma_f32_16x16x32_bf16 v[36:39], v[84:87], v[182:185], 0
	v_mfma_f32_16x16x32_bf16 v[32:35], v[92:95], v[182:185], 0
	v_mfma_f32_16x16x32_bf16 v[20:23], v[84:87], v[190:193], 0
	v_mfma_f32_16x16x32_bf16 v[16:19], v[92:95], v[190:193], 0
	v_mfma_f32_16x16x32_bf16 v[0:3], v[84:87], v[198:201], 0
	v_mfma_f32_16x16x32_bf16 v[4:7], v[92:95], v[198:201], 0
	v_mfma_f32_16x16x32_bf16 v[52:55], v[88:91], v[178:181], v[52:55]
	v_mfma_f32_16x16x32_bf16 v[48:51], v[96:99], v[178:181], v[48:51]
	v_mfma_f32_16x16x32_bf16 v[36:39], v[88:91], v[186:189], v[36:39]
	v_mfma_f32_16x16x32_bf16 v[32:35], v[96:99], v[186:189], v[32:35]
	v_mfma_f32_16x16x32_bf16 v[20:23], v[88:91], v[194:197], v[20:23]
	v_mfma_f32_16x16x32_bf16 v[16:19], v[96:99], v[194:197], v[16:19]
	v_mfma_f32_16x16x32_bf16 v[0:3], v[88:91], v[202:205], v[0:3]
	v_mfma_f32_16x16x32_bf16 v[4:7], v[96:99], v[202:205], v[4:7]
	s_setprio 0
	s_barrier
	v_add_u32_e32 v76, s37, v208
	v_add_u32_e32 v96, s26, v208
	ds_read_b128 v[64:67], v76
	ds_read_b128 v[68:71], v76 offset:1024
	ds_read_b128 v[72:75], v76 offset:2048
	ds_read_b128 v[76:79], v76 offset:3072
	ds_read_b128 v[84:87], v96
	ds_read_b128 v[88:91], v96 offset:1024
	ds_read_b128 v[92:95], v96 offset:2048
	ds_read_b128 v[96:99], v96 offset:3072
	s_add_u32 s6, s6, 0x80000
	s_addc_u32 s7, s7, 0
	s_mov_b32 m0, s22
	v_lshl_add_u64 v[226:227], s[6:7], 0, v[160:161]
	ds_read_b128 v[174:177], v211 offset:32768
	ds_read_b128 v[178:181], v211 offset:33792
	ds_read_b128 v[182:185], v211 offset:34816
	ds_read_b128 v[186:189], v211 offset:35840
	ds_read_b128 v[190:193], v211 offset:36864
	ds_read_b128 v[194:197], v211 offset:37888
	ds_read_b128 v[198:201], v211 offset:38912
	ds_read_b128 v[202:205], v211 offset:39936
	global_load_lds_dwordx4 v[226:227], off
	v_lshl_add_u64 v[226:227], s[6:7], 0, v[164:165]
	s_mov_b32 m0, s23
	s_nop 0
	global_load_lds_dwordx4 v[226:227], off
	s_waitcnt vmcnt(8) lgkmcnt(0)
	s_barrier
	s_setprio 1
	v_mfma_f32_16x16x32_bf16 v[156:159], v[64:67], v[174:177], v[156:159]
	v_mfma_f32_16x16x32_bf16 v[148:151], v[72:75], v[174:177], v[148:151]
	v_mfma_f32_16x16x32_bf16 v[140:143], v[64:67], v[182:185], v[140:143]
	v_mfma_f32_16x16x32_bf16 v[136:139], v[72:75], v[182:185], v[136:139]
	v_mfma_f32_16x16x32_bf16 v[124:127], v[64:67], v[190:193], v[124:127]
	v_mfma_f32_16x16x32_bf16 v[120:123], v[72:75], v[190:193], v[120:123]
	v_mfma_f32_16x16x32_bf16 v[108:111], v[64:67], v[198:201], v[108:111]
	v_mfma_f32_16x16x32_bf16 v[104:107], v[72:75], v[198:201], v[104:107]
	v_mfma_f32_16x16x32_bf16 v[156:159], v[68:71], v[178:181], v[156:159]
	v_mfma_f32_16x16x32_bf16 v[148:151], v[76:79], v[178:181], v[148:151]
	v_mfma_f32_16x16x32_bf16 v[140:143], v[68:71], v[186:189], v[140:143]
	v_mfma_f32_16x16x32_bf16 v[136:139], v[76:79], v[186:189], v[136:139]
	v_mfma_f32_16x16x32_bf16 v[124:127], v[68:71], v[194:197], v[124:127]
	v_mfma_f32_16x16x32_bf16 v[120:123], v[76:79], v[194:197], v[120:123]
	v_mfma_f32_16x16x32_bf16 v[108:111], v[68:71], v[202:205], v[108:111]
	v_mfma_f32_16x16x32_bf16 v[104:107], v[76:79], v[202:205], v[104:107]
	s_setprio 0
	s_setprio 1
	v_mfma_f32_16x16x32_bf16 v[152:155], v[84:87], v[174:177], v[152:155]
	v_mfma_f32_16x16x32_bf16 v[144:147], v[92:95], v[174:177], v[144:147]
	v_mfma_f32_16x16x32_bf16 v[132:135], v[84:87], v[182:185], v[132:135]
	v_mfma_f32_16x16x32_bf16 v[128:131], v[92:95], v[182:185], v[128:131]
	v_mfma_f32_16x16x32_bf16 v[116:119], v[84:87], v[190:193], v[116:119]
	v_mfma_f32_16x16x32_bf16 v[112:115], v[92:95], v[190:193], v[112:115]
	v_mfma_f32_16x16x32_bf16 v[80:83], v[84:87], v[198:201], v[80:83]
	v_mfma_f32_16x16x32_bf16 v[100:103], v[92:95], v[198:201], v[100:103]
	v_mfma_f32_16x16x32_bf16 v[152:155], v[88:91], v[178:181], v[152:155]
	v_mfma_f32_16x16x32_bf16 v[144:147], v[96:99], v[178:181], v[144:147]
	v_mfma_f32_16x16x32_bf16 v[132:135], v[88:91], v[186:189], v[132:135]
	v_mfma_f32_16x16x32_bf16 v[128:131], v[96:99], v[186:189], v[128:131]
	v_mfma_f32_16x16x32_bf16 v[116:119], v[88:91], v[194:197], v[116:119]
	v_mfma_f32_16x16x32_bf16 v[112:115], v[96:99], v[194:197], v[112:115]
	v_mfma_f32_16x16x32_bf16 v[80:83], v[88:91], v[202:205], v[80:83]
	v_mfma_f32_16x16x32_bf16 v[100:103], v[96:99], v[202:205], v[100:103]
	s_setprio 0
	s_barrier
; #define PG8_STAGE(bufoff, gbase, voff) do { _Pragma("unroll") for (int _i = 0; _i < 2; ++_i) \
;         __builtin_amdgcn_global_load_lds((const unsigned*)((const char*)(gbase) + (voff)[_i]), (LAS unsigned*)(lds + (bufoff) + ldsw + _i * 8192), 16, 0, 0); } while (0)
; #define PG8_LDA(dst, b, h) do { _Pragma("unroll") for (int m = 0; m < 4; ++m) _Pragma("unroll") for (int k = 0; k < 2; ++k) dst[m][k] = *(const LAS bf16x8*)(lds + PG8_SA(b, h) + aoff + m * 2048 + k * 1024); } while (0)
; #define PG8_MMA(ai, bj, At, Bt) do { __builtin_amdgcn_s_setprio(1); _Pragma("unroll") for (int m = 0; m < 4; ++m) _Pragma("unroll") for (int n = 0; n < 2; ++n) _Pragma("unroll") for (int k = 0; k < 2; ++k) \
;         acc[ai][bj][m][n] = __builtin_amdgcn_mfma_f32_16x16x32_bf16(Bt[n][k], At[m][k], acc[ai][bj][m][n], 0, 0, 0); __builtin_amdgcn_s_setprio(0); } while (0)
; #define PG8_WAIT_V(n) asm volatile("s_waitcnt vmcnt(" #n ")" ::: "memory")
; #define PG8_WAIT_L(n) asm volatile("s_waitcnt lgkmcnt(" #n ")" ::: "memory")
; #define PG8_BAR __builtin_amdgcn_s_barrier()
; #define PG8_SCHED __builtin_amdgcn_sched_barrier(0)
; template <class Epi, class Sched>
; __device__ __forceinline__ void gemm_phase(LAS unsigned char* lds, const Gemm g, const Sched& S, const Epi& E) {
;     ...
;             PG8_LDA(At, 1, 1); PG8_STAGE(PG8_SB(1, 0), b3, voffB); PG8_STAGE(PG8_SB(1, 1), b3 + hstepB, voffB); PG8_STAGE(PG8_SA(1, 0), a3, voffA);
;             PG8_WAIT_V(8); PG8_WAIT_L(0); PG8_BAR; PG8_MMA(1, 0, At, B0); PG8_MMA(1, 1, At, B1); PG8_BAR; PG8_SCHED;
	s_add_i32 s6, s37, s14
	v_lshl_add_u64 v[218:219], v[218:219], 0, s[48:49]
	s_mov_b32 m0, s6
	ds_read_b128 v[174:177], v211 offset:49152
	ds_read_b128 v[178:181], v211 offset:50176
	ds_read_b128 v[182:185], v211 offset:51200
	ds_read_b128 v[186:189], v211 offset:52224
	ds_read_b128 v[190:193], v211 offset:53248
	ds_read_b128 v[194:197], v211 offset:54272
	ds_read_b128 v[198:201], v211 offset:55296
	ds_read_b128 v[202:205], v211 offset:56320
	global_load_lds_dwordx4 v[218:219], off
	s_add_i32 m0, s6, 0x2000
	s_add_u32 s4, s4, 0x80080
	v_lshl_add_u64 v[218:219], v[220:221], 0, s[48:49]
	s_addc_u32 s5, s5, 0
	s_add_i32 s6, s26, s14
	global_load_lds_dwordx4 v[218:219], off
	v_lshl_add_u64 v[218:219], s[4:5], 0, v[162:163]
	s_mov_b32 m0, s6
	s_nop 0
	global_load_lds_dwordx4 v[218:219], off
	v_lshl_add_u64 v[218:219], s[4:5], 0, v[166:167]
	s_add_i32 m0, s6, 0x2000
	s_nop 0
	global_load_lds_dwordx4 v[218:219], off
	v_lshl_add_u64 v[218:219], v[222:223], 0, s[48:49]
	s_mov_b32 m0, s45
	s_nop 0
	global_load_lds_dwordx4 v[218:219], off
	v_lshl_add_u64 v[218:219], v[224:225], 0, s[48:49]
	s_mov_b32 m0, s64
	s_nop 0
	global_load_lds_dwordx4 v[218:219], off
	s_waitcnt vmcnt(8) lgkmcnt(0)
	s_barrier
	s_setprio 1
	v_mfma_f32_16x16x32_bf16 v[60:63], v[64:67], v[174:177], v[60:63]
	v_mfma_f32_16x16x32_bf16 v[56:59], v[72:75], v[174:177], v[56:59]
	v_mfma_f32_16x16x32_bf16 v[44:47], v[64:67], v[182:185], v[44:47]
	v_mfma_f32_16x16x32_bf16 v[40:43], v[72:75], v[182:185], v[40:43]
	v_mfma_f32_16x16x32_bf16 v[28:31], v[64:67], v[190:193], v[28:31]
	v_mfma_f32_16x16x32_bf16 v[24:27], v[72:75], v[190:193], v[24:27]
	v_mfma_f32_16x16x32_bf16 v[12:15], v[64:67], v[198:201], v[12:15]
	v_mfma_f32_16x16x32_bf16 v[8:11], v[72:75], v[198:201], v[8:11]
	v_mfma_f32_16x16x32_bf16 v[60:63], v[68:71], v[178:181], v[60:63]
	v_mfma_f32_16x16x32_bf16 v[56:59], v[76:79], v[178:181], v[56:59]
	v_mfma_f32_16x16x32_bf16 v[44:47], v[68:71], v[186:189], v[44:47]
	v_mfma_f32_16x16x32_bf16 v[40:43], v[76:79], v[186:189], v[40:43]
	v_mfma_f32_16x16x32_bf16 v[28:31], v[68:71], v[194:197], v[28:31]
	v_mfma_f32_16x16x32_bf16 v[24:27], v[76:79], v[194:197], v[24:27]
	v_mfma_f32_16x16x32_bf16 v[12:15], v[68:71], v[202:205], v[12:15]
	v_mfma_f32_16x16x32_bf16 v[8:11], v[76:79], v[202:205], v[8:11]
	s_setprio 0
	s_setprio 1
	v_mfma_f32_16x16x32_bf16 v[52:55], v[84:87], v[174:177], v[52:55]
	v_mfma_f32_16x16x32_bf16 v[48:51], v[92:95], v[174:177], v[48:51]
	v_mfma_f32_16x16x32_bf16 v[36:39], v[84:87], v[182:185], v[36:39]
	v_mfma_f32_16x16x32_bf16 v[32:35], v[92:95], v[182:185], v[32:35]
	v_mfma_f32_16x16x32_bf16 v[20:23], v[84:87], v[190:193], v[20:23]
	v_mfma_f32_16x16x32_bf16 v[16:19], v[92:95], v[190:193], v[16:19]
	v_mfma_f32_16x16x32_bf16 v[0:3], v[84:87], v[198:201], v[0:3]
	v_mfma_f32_16x16x32_bf16 v[4:7], v[92:95], v[198:201], v[4:7]
	v_mfma_f32_16x16x32_bf16 v[52:55], v[88:91], v[178:181], v[52:55]
	v_mfma_f32_16x16x32_bf16 v[48:51], v[96:99], v[178:181], v[48:51]
	v_mfma_f32_16x16x32_bf16 v[36:39], v[88:91], v[186:189], v[36:39]
	v_mfma_f32_16x16x32_bf16 v[32:35], v[96:99], v[186:189], v[32:35]
	v_mfma_f32_16x16x32_bf16 v[20:23], v[88:91], v[194:197], v[20:23]
	v_mfma_f32_16x16x32_bf16 v[16:19], v[96:99], v[194:197], v[16:19]
	v_mfma_f32_16x16x32_bf16 v[0:3], v[88:91], v[202:205], v[0:3]
	v_mfma_f32_16x16x32_bf16 v[4:7], v[96:99], v[202:205], v[4:7]
	s_setprio 0
	s_barrier
	s_add_i32 s62, s62, 2
	s_add_u32 s0, s0, 0x100
	s_addc_u32 s1, s1, 0
	s_add_u32 s60, s60, 0x100
	s_addc_u32 s61, s61, 0
	s_cmp_gt_u32 s62, 29

; #define PG8_STAGE(bufoff, gbase, voff) do { _Pragma("unroll") for (int _i = 0; _i < 2; ++_i) \
;         __builtin_amdgcn_global_load_lds((const unsigned*)((const char*)(gbase) + (voff)[_i]), (LAS unsigned*)(lds + (bufoff) + ldsw + _i * 8192), 16, 0, 0); } while (0)
; #define PG8_LDA(dst, b, h) do { _Pragma("unroll") for (int m = 0; m < 4; ++m) _Pragma("unroll") for (int k = 0; k < 2; ++k) dst[m][k] = *(const LAS bf16x8*)(lds + PG8_SA(b, h) + aoff + m * 2048 + k * 1024); } while (0)
; #define PG8_LDB(dst, b, h) do { _Pragma("unroll") for (int n = 0; n < 2; ++n) _Pragma("unroll") for (int k = 0; k < 2; ++k) dst[n][k] = *(const LAS bf16x8*)(lds + PG8_SB(b, h) + boff + n * 2048 + k * 1024); } while (0)
; #define PG8_MMA(ai, bj, At, Bt) do { __builtin_amdgcn_s_setprio(1); _Pragma("unroll") for (int m = 0; m < 4; ++m) _Pragma("unroll") for (int n = 0; n < 2; ++n) _Pragma("unroll") for (int k = 0; k < 2; ++k) \
;         acc[ai][bj][m][n] = __builtin_amdgcn_mfma_f32_16x16x32_bf16(Bt[n][k], At[m][k], acc[ai][bj][m][n], 0, 0, 0); __builtin_amdgcn_s_setprio(0); } while (0)
; #define PG8_WAIT_V(n) asm volatile("s_waitcnt vmcnt(" #n ")" ::: "memory")
; #define PG8_WAIT_L(n) asm volatile("s_waitcnt lgkmcnt(" #n ")" ::: "memory")
; #define PG8_BAR __builtin_amdgcn_s_barrier()
; #define PG8_SCHED __builtin_amdgcn_sched_barrier(0)
; template <class Epi, class Sched>
; __device__ __forceinline__ void gemm_phase(LAS unsigned char* lds, const Gemm g, const Sched& S, const Epi& E) {
;     ...
;             const char* a1 = cA + (size_t)(t + 1) * kstep;
;             const char* a2 = last ? nA : cA + (size_t)(t + 2) * kstep; const char* b2 = last ? nB : cB + (size_t)(t + 2) * kstep;
;             const char* a3 = a2 + kstep; const char* b3 = b2 + kstep;
;             PG8_LDB(B0, 0, 0); PG8_LDB(B1, 0, 1); PG8_SCHED; PG8_LDA(At, 0, 0); PG8_STAGE(PG8_SA(1, 1), a1 + hstepA, voffA);
;             PG8_WAIT_V(8); PG8_WAIT_L(0); PG8_BAR; PG8_MMA(0, 0, At, B0); PG8_MMA(0, 1, At, B1); PG8_BAR; PG8_SCHED;
;             PG8_LDA(At, 0, 1); PG8_STAGE(PG8_SB(0, 0), b2, voffB); PG8_STAGE(PG8_SB(0, 1), b2 + hstepB, voffB); PG8_STAGE(PG8_SA(0, 0), a2, voffA);
;     ...
;                 for (int m = 0; m < 4; ++m)
; #pragma unroll
;                     for (int n = 0; n < 2; ++n) acc[a][b][m][n] = (f32x4){0.f, 0.f, 0.f, 0.f};
.LBB0_1076:
	s_mov_b32 s1, -2
	s_mov_b64 s[4:5], s[20:21]
	ds_read_b128 v[128:131], v193
	ds_read_b128 v[132:135], v193 offset:1024
	ds_read_b128 v[148:151], v193 offset:2048
	ds_read_b128 v[152:155], v193 offset:3072
	ds_read_b128 v[156:159], v194
	ds_read_b128 v[160:163], v194 offset:1024
	ds_read_b128 v[164:167], v194 offset:2048
	ds_read_b128 v[168:171], v194 offset:3072
	s_add_u32 s30, s24, 0x100
	s_addc_u32 s31, s25, 0
	s_cmpk_eq_i32 s1, 0x5c
	s_cselect_b32 s39, s23, s31
	s_cselect_b32 s38, s22, s30
	s_cselect_b32 s35, s7, s5
	s_cselect_b32 s34, s6, s4
	v_lshl_add_u64 v[214:215], s[24:25], 0, v[144:145]
	s_add_i32 m0, s28, 0xc000
	ds_read_b128 v[172:175], v195
	ds_read_b128 v[176:179], v195 offset:1024
	ds_read_b128 v[180:183], v195 offset:2048
	ds_read_b128 v[184:187], v195 offset:3072
	ds_read_b128 v[198:201], v195 offset:4096
	ds_read_b128 v[202:205], v195 offset:5120
	ds_read_b128 v[206:209], v195 offset:6144
	ds_read_b128 v[210:213], v195 offset:7168
	global_load_lds_dwordx4 v[214:215], off
	v_lshl_add_u64 v[214:215], s[24:25], 0, v[146:147]
	s_add_i32 m0, s28, 0xe000
	s_nop 0
	global_load_lds_dwordx4 v[214:215], off
	s_waitcnt vmcnt(8) lgkmcnt(0)
	s_barrier
	s_setprio 1
	v_mfma_f32_16x16x32_bf16 v[124:127], v[128:131], v[172:175], 0
	v_mfma_f32_16x16x32_bf16 v[120:123], v[148:151], v[172:175], 0
	v_mfma_f32_16x16x32_bf16 v[108:111], v[128:131], v[180:183], 0
	v_mfma_f32_16x16x32_bf16 v[104:107], v[148:151], v[180:183], 0
	v_mfma_f32_16x16x32_bf16 v[92:95], v[128:131], v[198:201], 0
	v_mfma_f32_16x16x32_bf16 v[88:91], v[148:151], v[198:201], 0
	v_mfma_f32_16x16x32_bf16 v[76:79], v[128:131], v[206:209], 0
	v_mfma_f32_16x16x32_bf16 v[72:75], v[148:151], v[206:209], 0
	v_mfma_f32_16x16x32_bf16 v[124:127], v[132:135], v[176:179], v[124:127]
	v_mfma_f32_16x16x32_bf16 v[120:123], v[152:155], v[176:179], v[120:123]
	v_mfma_f32_16x16x32_bf16 v[108:111], v[132:135], v[184:187], v[108:111]
	v_mfma_f32_16x16x32_bf16 v[104:107], v[152:155], v[184:187], v[104:107]
	v_mfma_f32_16x16x32_bf16 v[92:95], v[132:135], v[202:205], v[92:95]
	v_mfma_f32_16x16x32_bf16 v[88:91], v[152:155], v[202:205], v[88:91]
	v_mfma_f32_16x16x32_bf16 v[76:79], v[132:135], v[210:213], v[76:79]
	v_mfma_f32_16x16x32_bf16 v[72:75], v[152:155], v[210:213], v[72:75]
	s_setprio 0
	s_setprio 1
	v_mfma_f32_16x16x32_bf16 v[116:119], v[156:159], v[172:175], 0
	v_mfma_f32_16x16x32_bf16 v[112:115], v[164:167], v[172:175], 0
	v_mfma_f32_16x16x32_bf16 v[100:103], v[156:159], v[180:183], 0
	v_mfma_f32_16x16x32_bf16 v[96:99], v[164:167], v[180:183], 0
	v_mfma_f32_16x16x32_bf16 v[84:87], v[156:159], v[198:201], 0
	v_mfma_f32_16x16x32_bf16 v[80:83], v[164:167], v[198:201], 0
	v_mfma_f32_16x16x32_bf16 v[68:71], v[156:159], v[206:209], 0
	v_mfma_f32_16x16x32_bf16 v[64:67], v[164:167], v[206:209], 0
	v_mfma_f32_16x16x32_bf16 v[116:119], v[160:163], v[176:179], v[116:119]
	v_mfma_f32_16x16x32_bf16 v[112:115], v[168:171], v[176:179], v[112:115]
	v_mfma_f32_16x16x32_bf16 v[100:103], v[160:163], v[184:187], v[100:103]
	v_mfma_f32_16x16x32_bf16 v[96:99], v[168:171], v[184:187], v[96:99]
	v_mfma_f32_16x16x32_bf16 v[84:87], v[160:163], v[202:205], v[84:87]
	v_mfma_f32_16x16x32_bf16 v[80:83], v[168:171], v[202:205], v[80:83]
	v_mfma_f32_16x16x32_bf16 v[68:71], v[160:163], v[210:213], v[68:71]
	v_mfma_f32_16x16x32_bf16 v[64:67], v[168:171], v[210:213], v[64:67]
	s_setprio 0
	s_barrier
	s_add_i32 s12, s33, s27
	v_lshl_add_u64 v[214:215], s[34:35], 0, v[138:139]
	s_mov_b32 m0, s12
	ds_read_b128 v[172:175], v195 offset:16384
	ds_read_b128 v[176:179], v195 offset:17408
	ds_read_b128 v[180:183], v195 offset:18432
	ds_read_b128 v[184:187], v195 offset:19456
	ds_read_b128 v[198:201], v195 offset:20480
	ds_read_b128 v[202:205], v195 offset:21504
	ds_read_b128 v[206:209], v195 offset:22528
	ds_read_b128 v[210:213], v195 offset:23552
	global_load_lds_dwordx4 v[214:215], off
	s_add_i32 m0, s12, 0x2000
	s_add_u32 s12, s34, 0x180000
	v_lshl_add_u64 v[216:217], s[34:35], 0, v[142:143]
	s_addc_u32 s13, s35, 0
	s_add_i32 s24, s36, s27
	global_load_lds_dwordx4 v[216:217], off
	v_lshl_add_u64 v[218:219], s[12:13], 0, v[138:139]
	s_mov_b32 m0, s24
	v_lshl_add_u64 v[220:221], s[38:39], 0, v[140:141]
	global_load_lds_dwordx4 v[218:219], off
	v_lshl_add_u64 v[218:219], s[12:13], 0, v[142:143]
	s_add_i32 m0, s24, 0x2000
	s_nop 0
	global_load_lds_dwordx4 v[218:219], off
	v_lshl_add_u64 v[218:219], s[38:39], 0, v[136:137]
	s_mov_b32 m0, s28
	s_nop 0
	global_load_lds_dwordx4 v[218:219], off
	s_mov_b32 m0, s40
	s_nop 0
	global_load_lds_dwordx4 v[220:221], off
	s_waitcnt vmcnt(8) lgkmcnt(0)
	s_barrier
; #define PG8_STAGE(bufoff, gbase, voff) do { _Pragma("unroll") for (int _i = 0; _i < 2; ++_i) \
;         __builtin_amdgcn_global_load_lds((const unsigned*)((const char*)(gbase) + (voff)[_i]), (LAS unsigned*)(lds + (bufoff) + ldsw + _i * 8192), 16, 0, 0); } while (0)
; #define PG8_LDA(dst, b, h) do { _Pragma("unroll") for (int m = 0; m < 4; ++m) _Pragma("unroll") for (int k = 0; k < 2; ++k) dst[m][k] = *(const LAS bf16x8*)(lds + PG8_SA(b, h) + aoff + m * 2048 + k * 1024); } while (0)
; #define PG8_LDB(dst, b, h) do { _Pragma("unroll") for (int n = 0; n < 2; ++n) _Pragma("unroll") for (int k = 0; k < 2; ++k) dst[n][k] = *(const LAS bf16x8*)(lds + PG8_SB(b, h) + boff + n * 2048 + k * 1024); } while (0)
; #define PG8_MMA(ai, bj, At, Bt) do { __builtin_amdgcn_s_setprio(1); _Pragma("unroll") for (int m = 0; m < 4; ++m) _Pragma("unroll") for (int n = 0; n < 2; ++n) _Pragma("unroll") for (int k = 0; k < 2; ++k) \
;         acc[ai][bj][m][n] = __builtin_amdgcn_mfma_f32_16x16x32_bf16(Bt[n][k], At[m][k], acc[ai][bj][m][n], 0, 0, 0); __builtin_amdgcn_s_setprio(0); } while (0)
; #define PG8_WAIT_V(n) asm volatile("s_waitcnt vmcnt(" #n ")" ::: "memory")
; #define PG8_WAIT_L(n) asm volatile("s_waitcnt lgkmcnt(" #n ")" ::: "memory")
; #define PG8_BAR __builtin_amdgcn_s_barrier()
; #define PG8_SCHED __builtin_amdgcn_sched_barrier(0)
; template <class Epi, class Sched>
; __device__ __forceinline__ void gemm_phase(LAS unsigned char* lds, const Gemm g, const Sched& S, const Epi& E) {
;     ...
;             PG8_WAIT_V(8); PG8_WAIT_L(0); PG8_BAR; PG8_MMA(1, 0, At, B0); PG8_MMA(1, 1, At, B1); PG8_BAR; PG8_SCHED;
;             PG8_LDB(B0, 1, 0); PG8_LDB(B1, 1, 1); PG8_SCHED; PG8_LDA(At, 1, 0); PG8_STAGE(PG8_SA(0, 1), a2 + hstepA, voffA);
;             PG8_WAIT_V(8); PG8_WAIT_L(0); PG8_BAR; PG8_MMA(0, 0, At, B0); PG8_MMA(0, 1, At, B1); PG8_BAR; PG8_SCHED;
	s_setprio 1
	v_mfma_f32_16x16x32_bf16 v[60:63], v[128:131], v[172:175], 0
	v_mfma_f32_16x16x32_bf16 v[56:59], v[148:151], v[172:175], 0
	v_mfma_f32_16x16x32_bf16 v[44:47], v[128:131], v[180:183], 0
	v_mfma_f32_16x16x32_bf16 v[40:43], v[148:151], v[180:183], 0
	v_mfma_f32_16x16x32_bf16 v[28:31], v[128:131], v[198:201], 0
	v_mfma_f32_16x16x32_bf16 v[24:27], v[148:151], v[198:201], 0
	v_mfma_f32_16x16x32_bf16 v[12:15], v[128:131], v[206:209], 0
	v_mfma_f32_16x16x32_bf16 v[8:11], v[148:151], v[206:209], 0
	v_mfma_f32_16x16x32_bf16 v[60:63], v[132:135], v[176:179], v[60:63]
	v_mfma_f32_16x16x32_bf16 v[56:59], v[152:155], v[176:179], v[56:59]
	v_mfma_f32_16x16x32_bf16 v[44:47], v[132:135], v[184:187], v[44:47]
	v_mfma_f32_16x16x32_bf16 v[40:43], v[152:155], v[184:187], v[40:43]
	v_mfma_f32_16x16x32_bf16 v[28:31], v[132:135], v[202:205], v[28:31]
	v_mfma_f32_16x16x32_bf16 v[24:27], v[152:155], v[202:205], v[24:27]
	v_mfma_f32_16x16x32_bf16 v[12:15], v[132:135], v[210:213], v[12:15]
	v_mfma_f32_16x16x32_bf16 v[8:11], v[152:155], v[210:213], v[8:11]
	s_setprio 0
	s_setprio 1
	v_mfma_f32_16x16x32_bf16 v[52:55], v[156:159], v[172:175], 0
	v_mfma_f32_16x16x32_bf16 v[48:51], v[164:167], v[172:175], 0
	v_mfma_f32_16x16x32_bf16 v[36:39], v[156:159], v[180:183], 0
	v_mfma_f32_16x16x32_bf16 v[32:35], v[164:167], v[180:183], 0
	v_mfma_f32_16x16x32_bf16 v[20:23], v[156:159], v[198:201], 0
	v_mfma_f32_16x16x32_bf16 v[16:19], v[164:167], v[198:201], 0
	v_mfma_f32_16x16x32_bf16 v[4:7], v[156:159], v[206:209], 0
	v_mfma_f32_16x16x32_bf16 v[0:3], v[164:167], v[206:209], 0
	v_mfma_f32_16x16x32_bf16 v[52:55], v[160:163], v[176:179], v[52:55]
	v_mfma_f32_16x16x32_bf16 v[48:51], v[168:171], v[176:179], v[48:51]
	v_mfma_f32_16x16x32_bf16 v[36:39], v[160:163], v[184:187], v[36:39]
	v_mfma_f32_16x16x32_bf16 v[32:35], v[168:171], v[184:187], v[32:35]
	v_mfma_f32_16x16x32_bf16 v[20:23], v[160:163], v[202:205], v[20:23]
	v_mfma_f32_16x16x32_bf16 v[16:19], v[168:171], v[202:205], v[16:19]
	v_mfma_f32_16x16x32_bf16 v[4:7], v[160:163], v[210:213], v[4:7]
	v_mfma_f32_16x16x32_bf16 v[0:3], v[168:171], v[210:213], v[0:3]
	s_setprio 0
	s_barrier
	v_add_u32_e32 v152, s37, v190
	v_add_u32_e32 v168, s26, v190
	ds_read_b128 v[128:131], v152
	ds_read_b128 v[132:135], v152 offset:1024
	ds_read_b128 v[148:151], v152 offset:2048
	ds_read_b128 v[152:155], v152 offset:3072
	ds_read_b128 v[156:159], v168
	ds_read_b128 v[160:163], v168 offset:1024
	ds_read_b128 v[164:167], v168 offset:2048
	ds_read_b128 v[168:171], v168 offset:3072
	s_add_u32 s12, s38, 0x180000
	s_addc_u32 s13, s39, 0
	s_mov_b32 m0, s41
	v_lshl_add_u64 v[222:223], s[12:13], 0, v[136:137]
	ds_read_b128 v[172:175], v195 offset:32768
	ds_read_b128 v[176:179], v195 offset:33792
	ds_read_b128 v[180:183], v195 offset:34816
	ds_read_b128 v[184:187], v195 offset:35840
	ds_read_b128 v[198:201], v195 offset:36864
	ds_read_b128 v[202:205], v195 offset:37888
	ds_read_b128 v[206:209], v195 offset:38912
	ds_read_b128 v[210:213], v195 offset:39936
	global_load_lds_dwordx4 v[222:223], off
	v_lshl_add_u64 v[222:223], s[12:13], 0, v[140:141]
	s_mov_b32 m0, s42
	s_nop 0
	global_load_lds_dwordx4 v[222:223], off
	s_waitcnt vmcnt(8) lgkmcnt(0)
	s_barrier
	s_setprio 1
	v_mfma_f32_16x16x32_bf16 v[124:127], v[128:131], v[172:175], v[124:127]
	v_mfma_f32_16x16x32_bf16 v[120:123], v[148:151], v[172:175], v[120:123]
	v_mfma_f32_16x16x32_bf16 v[108:111], v[128:131], v[180:183], v[108:111]
	v_mfma_f32_16x16x32_bf16 v[104:107], v[148:151], v[180:183], v[104:107]
	v_mfma_f32_16x16x32_bf16 v[92:95], v[128:131], v[198:201], v[92:95]
	v_mfma_f32_16x16x32_bf16 v[88:91], v[148:151], v[198:201], v[88:91]
	v_mfma_f32_16x16x32_bf16 v[76:79], v[128:131], v[206:209], v[76:79]
	v_mfma_f32_16x16x32_bf16 v[72:75], v[148:151], v[206:209], v[72:75]
	v_mfma_f32_16x16x32_bf16 v[124:127], v[132:135], v[176:179], v[124:127]
	v_mfma_f32_16x16x32_bf16 v[120:123], v[152:155], v[176:179], v[120:123]
	v_mfma_f32_16x16x32_bf16 v[108:111], v[132:135], v[184:187], v[108:111]
	v_mfma_f32_16x16x32_bf16 v[104:107], v[152:155], v[184:187], v[104:107]
	v_mfma_f32_16x16x32_bf16 v[92:95], v[132:135], v[202:205], v[92:95]
	v_mfma_f32_16x16x32_bf16 v[88:91], v[152:155], v[202:205], v[88:91]
	v_mfma_f32_16x16x32_bf16 v[76:79], v[132:135], v[210:213], v[76:79]
	v_mfma_f32_16x16x32_bf16 v[72:75], v[152:155], v[210:213], v[72:75]
	s_setprio 0
	s_setprio 1
	v_mfma_f32_16x16x32_bf16 v[116:119], v[156:159], v[172:175], v[116:119]
	v_mfma_f32_16x16x32_bf16 v[112:115], v[164:167], v[172:175], v[112:115]
	v_mfma_f32_16x16x32_bf16 v[100:103], v[156:159], v[180:183], v[100:103]
	v_mfma_f32_16x16x32_bf16 v[96:99], v[164:167], v[180:183], v[96:99]
	v_mfma_f32_16x16x32_bf16 v[84:87], v[156:159], v[198:201], v[84:87]
	v_mfma_f32_16x16x32_bf16 v[80:83], v[164:167], v[198:201], v[80:83]
	v_mfma_f32_16x16x32_bf16 v[68:71], v[156:159], v[206:209], v[68:71]
	v_mfma_f32_16x16x32_bf16 v[64:67], v[164:167], v[206:209], v[64:67]
	v_mfma_f32_16x16x32_bf16 v[116:119], v[160:163], v[176:179], v[116:119]
	v_mfma_f32_16x16x32_bf16 v[112:115], v[168:171], v[176:179], v[112:115]
	v_mfma_f32_16x16x32_bf16 v[100:103], v[160:163], v[184:187], v[100:103]
	v_mfma_f32_16x16x32_bf16 v[96:99], v[168:171], v[184:187], v[96:99]
	v_mfma_f32_16x16x32_bf16 v[84:87], v[160:163], v[202:205], v[84:87]
	v_mfma_f32_16x16x32_bf16 v[80:83], v[168:171], v[202:205], v[80:83]
	v_mfma_f32_16x16x32_bf16 v[68:71], v[160:163], v[210:213], v[68:71]
	v_mfma_f32_16x16x32_bf16 v[64:67], v[168:171], v[210:213], v[64:67]
	s_setprio 0
	s_barrier
; #define PG8_STAGE(bufoff, gbase, voff) do { _Pragma("unroll") for (int _i = 0; _i < 2; ++_i) \
;         __builtin_amdgcn_global_load_lds((const unsigned*)((const char*)(gbase) + (voff)[_i]), (LAS unsigned*)(lds + (bufoff) + ldsw + _i * 8192), 16, 0, 0); } while (0)
; #define PG8_LDA(dst, b, h) do { _Pragma("unroll") for (int m = 0; m < 4; ++m) _Pragma("unroll") for (int k = 0; k < 2; ++k) dst[m][k] = *(const LAS bf16x8*)(lds + PG8_SA(b, h) + aoff + m * 2048 + k * 1024); } while (0)
; #define PG8_MMA(ai, bj, At, Bt) do { __builtin_amdgcn_s_setprio(1); _Pragma("unroll") for (int m = 0; m < 4; ++m) _Pragma("unroll") for (int n = 0; n < 2; ++n) _Pragma("unroll") for (int k = 0; k < 2; ++k) \
;         acc[ai][bj][m][n] = __builtin_amdgcn_mfma_f32_16x16x32_bf16(Bt[n][k], At[m][k], acc[ai][bj][m][n], 0, 0, 0); __builtin_amdgcn_s_setprio(0); } while (0)
; #define PG8_WAIT_V(n) asm volatile("s_waitcnt vmcnt(" #n ")" ::: "memory")
; #define PG8_WAIT_L(n) asm volatile("s_waitcnt lgkmcnt(" #n ")" ::: "memory")
; #define PG8_BAR __builtin_amdgcn_s_barrier()
; #define PG8_SCHED __builtin_amdgcn_sched_barrier(0)
; template <class Epi, class Sched>
; __device__ __forceinline__ void gemm_phase(LAS unsigned char* lds, const Gemm g, const Sched& S, const Epi& E) {
;     ...
;             PG8_LDA(At, 1, 1); PG8_STAGE(PG8_SB(1, 0), b3, voffB); PG8_STAGE(PG8_SB(1, 1), b3 + hstepB, voffB); PG8_STAGE(PG8_SA(1, 0), a3, voffA);
;             PG8_WAIT_V(8); PG8_WAIT_L(0); PG8_BAR; PG8_MMA(1, 0, At, B0); PG8_MMA(1, 1, At, B1); PG8_BAR; PG8_SCHED;
	s_add_i32 s12, s37, s27
	v_lshl_add_u64 v[214:215], v[214:215], 0, s[16:17]
	s_mov_b32 m0, s12
	ds_read_b128 v[172:175], v195 offset:49152
	ds_read_b128 v[176:179], v195 offset:50176
	ds_read_b128 v[180:183], v195 offset:51200
	ds_read_b128 v[184:187], v195 offset:52224
	ds_read_b128 v[198:201], v195 offset:53248
	ds_read_b128 v[202:205], v195 offset:54272
	ds_read_b128 v[206:209], v195 offset:55296
	ds_read_b128 v[210:213], v195 offset:56320
	global_load_lds_dwordx4 v[214:215], off
	s_add_i32 m0, s12, 0x2000
	s_add_u32 s12, s34, 0x180080
	v_lshl_add_u64 v[214:215], v[216:217], 0, s[16:17]
	s_addc_u32 s13, s35, 0
	s_add_i32 s24, s26, s27
	global_load_lds_dwordx4 v[214:215], off
	v_lshl_add_u64 v[214:215], s[12:13], 0, v[138:139]
	s_mov_b32 m0, s24
	s_nop 0
	global_load_lds_dwordx4 v[214:215], off
	v_lshl_add_u64 v[214:215], s[12:13], 0, v[142:143]
	s_add_i32 m0, s24, 0x2000
	s_nop 0
	global_load_lds_dwordx4 v[214:215], off
	v_lshl_add_u64 v[214:215], v[218:219], 0, s[16:17]
	s_mov_b32 m0, s46
	s_nop 0
	global_load_lds_dwordx4 v[214:215], off
	v_lshl_add_u64 v[214:215], v[220:221], 0, s[16:17]
	s_mov_b32 m0, s47
	s_nop 0
	global_load_lds_dwordx4 v[214:215], off
	s_waitcnt vmcnt(8) lgkmcnt(0)
	s_barrier
	s_setprio 1
	v_mfma_f32_16x16x32_bf16 v[60:63], v[128:131], v[172:175], v[60:63]
	v_mfma_f32_16x16x32_bf16 v[56:59], v[148:151], v[172:175], v[56:59]
	v_mfma_f32_16x16x32_bf16 v[44:47], v[128:131], v[180:183], v[44:47]
	v_mfma_f32_16x16x32_bf16 v[40:43], v[148:151], v[180:183], v[40:43]
	v_mfma_f32_16x16x32_bf16 v[28:31], v[128:131], v[198:201], v[28:31]
	v_mfma_f32_16x16x32_bf16 v[24:27], v[148:151], v[198:201], v[24:27]
	v_mfma_f32_16x16x32_bf16 v[12:15], v[128:131], v[206:209], v[12:15]
	v_mfma_f32_16x16x32_bf16 v[8:11], v[148:151], v[206:209], v[8:11]
	v_mfma_f32_16x16x32_bf16 v[60:63], v[132:135], v[176:179], v[60:63]
	v_mfma_f32_16x16x32_bf16 v[56:59], v[152:155], v[176:179], v[56:59]
	v_mfma_f32_16x16x32_bf16 v[44:47], v[132:135], v[184:187], v[44:47]
	v_mfma_f32_16x16x32_bf16 v[40:43], v[152:155], v[184:187], v[40:43]
	v_mfma_f32_16x16x32_bf16 v[28:31], v[132:135], v[202:205], v[28:31]
	v_mfma_f32_16x16x32_bf16 v[24:27], v[152:155], v[202:205], v[24:27]
	v_mfma_f32_16x16x32_bf16 v[12:15], v[132:135], v[210:213], v[12:15]
	v_mfma_f32_16x16x32_bf16 v[8:11], v[152:155], v[210:213], v[8:11]
	s_setprio 0
	s_setprio 1
	v_mfma_f32_16x16x32_bf16 v[52:55], v[156:159], v[172:175], v[52:55]
	v_mfma_f32_16x16x32_bf16 v[48:51], v[164:167], v[172:175], v[48:51]
	v_mfma_f32_16x16x32_bf16 v[36:39], v[156:159], v[180:183], v[36:39]
	v_mfma_f32_16x16x32_bf16 v[32:35], v[164:167], v[180:183], v[32:35]
	v_mfma_f32_16x16x32_bf16 v[20:23], v[156:159], v[198:201], v[20:23]
	v_mfma_f32_16x16x32_bf16 v[16:19], v[164:167], v[198:201], v[16:19]
	v_mfma_f32_16x16x32_bf16 v[4:7], v[156:159], v[206:209], v[4:7]
	v_mfma_f32_16x16x32_bf16 v[0:3], v[164:167], v[206:209], v[0:3]
	v_mfma_f32_16x16x32_bf16 v[52:55], v[160:163], v[176:179], v[52:55]
	v_mfma_f32_16x16x32_bf16 v[48:51], v[168:171], v[176:179], v[48:51]
	v_mfma_f32_16x16x32_bf16 v[36:39], v[160:163], v[184:187], v[36:39]
	v_mfma_f32_16x16x32_bf16 v[32:35], v[168:171], v[184:187], v[32:35]
	v_mfma_f32_16x16x32_bf16 v[20:23], v[160:163], v[202:205], v[20:23]
	v_mfma_f32_16x16x32_bf16 v[16:19], v[168:171], v[202:205], v[16:19]
	v_mfma_f32_16x16x32_bf16 v[4:7], v[160:163], v[210:213], v[4:7]
	v_mfma_f32_16x16x32_bf16 v[0:3], v[168:171], v[210:213], v[0:3]
	s_setprio 0
	s_barrier
	s_add_i32 s1, s1, 2
	s_add_u32 s4, s4, 0x100
	s_addc_u32 s5, s5, 0
	s_cmpk_gt_u32 s1, 0x5d
	s_mov_b64 s[24:25], s[30:31]
